# sp2: MLA q/kv up-projections as one fragment-major 1792-column problem on the hand GEMM (2 rounds, rr from w_in row sums, rope in epilogue); retkv tiles redistributed
# speedup vs baseline: 1.0065x; 1.0065x over previous
.Lg2_up_entry:
	s_waitcnt vmcnt(0) lgkmcnt(0)
	s_barrier
	v_mov_b32_e32 v2, 0x10200
	ds_read_b64 v[2:3], v2
	v_readlane_b32 s0, v246, 0
	v_lshrrev_b32_e32 v4, 6, v163
	v_and_b32_e32 v5, 63, v163
	s_and_b32 s1, s0, 7
	s_lshr_b32 s0, s0, 3
	s_lshr_b32 s68, s0, 3
	s_and_b32 s0, s0, 7
	s_lshl_b32 s0, s0, 3
	s_add_i32 s0, s0, s1
	s_cmp_lt_u32 s0, 32
	s_cselect_b32 s43, 1, 0
	s_min_u32 s1, s0, 32
	s_lshl_b32 s0, s0, 4
	s_add_i32 s0, s0, s1
	s_lshl_b32 s42, s0, 4
	v_readfirstlane_b32 s70, v4
	v_and_b32_e32 v6, 15, v5
	v_lshrrev_b32_e32 v7, 4, v5
	s_waitcnt lgkmcnt(0)
	v_readfirstlane_b32 s66, v2
	v_readfirstlane_b32 s67, v3
	s_lshl_b32 s62, s70, 10
	v_and_b32_e32 v8, 7, v6
	v_xor_b32_e32 v9, v7, v8
	v_lshlrev_b32_e32 v9, 4, v9
	v_lshl_add_u32 v156, v6, 7, v9
	v_add_u32_e32 v10, 4, v7
	v_xor_b32_e32 v10, v10, v8
	v_lshlrev_b32_e32 v10, 4, v10
	v_lshl_add_u32 v157, v6, 7, v10
	v_add_u32_e32 v158, 0x8800, v156
	v_add_u32_e32 v159, 0x8800, v157
	v_lshrrev_b32_e32 v11, 3, v163
	v_and_b32_e32 v12, 7, v163
	v_and_b32_e32 v13, 7, v11
	v_xor_b32_e32 v12, v12, v13
	v_lshlrev_b32_e32 v12, 4, v12
	s_mov_b32 s2, 0x3900
	v_mul_lo_u32 v11, v11, s2
	v_add_u32_e32 v162, v11, v12
	v_lshrrev_b32_e32 v11, 4, v163
	v_and_b32_e32 v12, 15, v163
	v_xor_b32_e32 v13, v12, v11
	v_lshlrev_b32_e32 v13, 4, v13
	v_lshl_add_u32 v247, v11, 8, v13
	s_mov_b32 s2, 0x600
	v_mul_lo_u32 v11, v11, s2
	v_lshl_add_u32 v252, v12, 4, v11
	v_add_u32_e32 v255, 0x8000, v247
	v_lshlrev_b32_e32 v11, 1, v4
	s_mov_b32 s2, 0x2000
	v_mul_lo_u32 v12, v11, s2
	v_lshl_add_u32 v160, v5, 4, v12
	v_add_u32_e32 v161, 0x2000, v160
	v_lshrrev_b32_e32 v12, 1, v7
	v_lshl_add_u32 v12, v11, 1, v12
	v_and_b32_e32 v13, 1, v7
	v_lshlrev_b32_e32 v13, 3, v13
	v_lshl_add_u32 v14, v6, 8, v13
	v_xor_b32_e32 v15, v12, v6
	v_lshlrev_b32_e32 v15, 4, v15
	v_add_u32_e32 v212, v14, v15
	v_add_u32_e32 v12, 2, v12
	v_xor_b32_e32 v15, v12, v6
	v_lshlrev_b32_e32 v15, 4, v15
	v_add_u32_e32 v213, v14, v15
	v_add_u32_e32 v253, 0x8000, v212
	v_add_u32_e32 v254, 0x8000, v213
	s_lshl_b32 s0, s42, 2
	s_add_u32 s0, s0, 0x16c00000
	s_add_u32 s0, s26, s0
	s_addc_u32 s1, s27, 0
	s_add_u32 s2, s0, 0x11000
	s_addc_u32 s3, s1, 0
	s_add_u32 s4, s2, 0x11000
	s_addc_u32 s5, s3, 0
	s_add_u32 s6, s4, 0x11000
	s_addc_u32 s7, s5, 0
	v_lshlrev_b32_e32 v8, 2, v163
	global_load_dword v10, v8, s[0:1]
	global_load_dword v11, v8, s[2:3]
	global_load_dword v12, v8, s[4:5]
	global_load_dword v13, v8, s[6:7]
	global_load_dword v14, v8, s[0:1] offset:1024
	global_load_dword v15, v8, s[2:3] offset:1024
	global_load_dword v16, v8, s[4:5] offset:1024
	global_load_dword v17, v8, s[6:7] offset:1024
	v_add_u32_e32 v9, 0x11000, v8
	s_waitcnt vmcnt(0)
	v_add_f32_e32 v10, v10, v11
	v_add_f32_e32 v12, v12, v13
	v_add_f32_e32 v14, v14, v15
	v_add_f32_e32 v16, v16, v17
	v_mul_f32_e32 v10, 0x3b800000, v10
	v_mul_f32_e32 v12, 0x3b800000, v12
	v_mul_f32_e32 v14, 0x3b800000, v14
	v_mul_f32_e32 v16, 0x3b800000, v16
	v_add_f32_e32 v10, 0x3727c5ac, v10
	v_add_f32_e32 v12, 0x3727c5ac, v12
	v_add_f32_e32 v14, 0x3727c5ac, v14
	v_add_f32_e32 v16, 0x3727c5ac, v16
	v_rsq_f32_e32 v10, v10
	v_rsq_f32_e32 v12, v12
	v_rsq_f32_e32 v14, v14
	v_rsq_f32_e32 v16, v16
	s_nop 0
	v_mul_f32_e32 v10, 0x3e16c740, v10
	v_mul_f32_e32 v14, 0x3e16c740, v14
	ds_write_b32 v9, v10
	ds_write_b32 v9, v12 offset:1088
	v_cmp_gt_u32_e32 vcc, 16, v163
	s_and_saveexec_b64 s[0:1], vcc
	ds_write_b32 v9, v14 offset:1024
	ds_write_b32 v9, v16 offset:2112
	s_mov_b64 exec, s[0:1]
	s_waitcnt lgkmcnt(0)
	s_mov_b32 s64, 0
.Lg2_up_tile:
	s_lshl_b32 s0, s64, 3
	s_add_i32 s38, s0, s68
	s_cmp_ge_u32 s38, 14
	s_cbranch_scc1 .Lg2_up_exit
	s_mov_b32 s69, s42
	s_mov_b32 s65, s43
	s_lshl_b32 s0, s38, 7
	s_mul_i32 s2, s69, 0x3900
	s_mul_hi_u32 s3, s69, 0x3900
	s_add_u32 s56, s26, s2
	s_addc_u32 s57, s27, s3
	s_cmp_lt_u32 s38, 6
	s_movk_i32 s2, 0x1e00
	s_cselect_b32 s2, 0x1c00, s2
	s_add_u32 s56, s56, s2
	s_addc_u32 s57, s57, 0
	s_lshl_b32 s2, s0, 9
	s_add_u32 s2, s2, 0xf960000
	s_add_u32 s58, s26, s2
	s_addc_u32 s59, s27, 0
	s_cmp_lt_u32 s38, 6
	s_cbranch_scc1 .Lg2_up_tb_q
	s_lshl_b32 s2, s69, 11
	s_sub_u32 s3, s38, 6
	s_lshl_b32 s3, s3, 8
	s_add_u32 s2, s2, s3
	s_add_u32 s2, s2, 0x14b00000
	s_branch .Lg2_up_tb_j
.Lg2_up_tb_q:
	s_mul_i32 s2, s69, 0x600
	s_lshl_b32 s3, s38, 8
	s_add_u32 s2, s2, s3
	s_add_u32 s2, s2, 0x13240000
.Lg2_up_tb_j:
	s_add_u32 s60, s26, s2
	s_addc_u32 s61, s27, 0
	s_cmp_eq_u32 s65, 0
	s_cbranch_scc1 .Lg2_up_k16
	s_add_u32 m0, s62, 0x0
	s_add_u32 s4, s56, 0x0
	s_addc_u32 s5, s57, 0
	global_load_lds_dwordx4 v162, s[4:5]
	s_add_u32 m0, s62, 0x1000
	s_add_u32 s4, s56, 0x72000
	s_addc_u32 s5, s57, 0
	global_load_lds_dwordx4 v162, s[4:5]
	s_add_u32 m0, s62, 0x2000
	s_add_u32 s4, s56, 0xe4000
	s_addc_u32 s5, s57, 0
	global_load_lds_dwordx4 v162, s[4:5]
	s_add_u32 m0, s62, 0x3000
	s_add_u32 s4, s56, 0x156000
	s_addc_u32 s5, s57, 0
	global_load_lds_dwordx4 v162, s[4:5]
	s_add_u32 m0, s62, 0x4000
	s_add_u32 s4, s56, 0x1c8000
	s_addc_u32 s5, s57, 0
	global_load_lds_dwordx4 v162, s[4:5]
	s_add_u32 m0, s62, 0x5000
	s_add_u32 s4, s56, 0x23a000
	s_addc_u32 s5, s57, 0
	global_load_lds_dwordx4 v162, s[4:5]
	s_add_u32 m0, s62, 0x6000
	s_add_u32 s4, s56, 0x2ac000
	s_addc_u32 s5, s57, 0
	global_load_lds_dwordx4 v162, s[4:5]
	s_add_u32 m0, s62, 0x7000
	s_add_u32 s4, s56, 0x31e000
	s_addc_u32 s5, s57, 0
	global_load_lds_dwordx4 v162, s[4:5]
	s_cmp_gt_u32 s70, 1
	s_cbranch_scc1 .Lg2_up_nodma_0
	s_add_u32 m0, s62, 0x8000
	s_add_u32 s4, s56, 0x390000
	s_addc_u32 s5, s57, 0
	global_load_lds_dwordx4 v162, s[4:5]

.Lg2_up_loop17:
	s_waitcnt vmcnt(0)
	s_barrier
	s_add_u32 s56, s56, 0x80
	s_addc_u32 s57, s57, 0
	s_add_u32 s58, s58, 0x800
	s_addc_u32 s59, s59, 0
	s_add_u32 m0, s62, 0x8800
	s_add_u32 s4, s56, 0x0
	s_addc_u32 s5, s57, 0
	global_load_lds_dwordx4 v162, s[4:5]
	s_add_u32 m0, s62, 0x9800
	s_add_u32 s4, s56, 0x72000
	s_addc_u32 s5, s57, 0
	global_load_lds_dwordx4 v162, s[4:5]
	s_add_u32 m0, s62, 0xa800
	s_add_u32 s4, s56, 0xe4000
	s_addc_u32 s5, s57, 0
	global_load_lds_dwordx4 v162, s[4:5]
	s_add_u32 m0, s62, 0xb800
	s_add_u32 s4, s56, 0x156000
	s_addc_u32 s5, s57, 0
	global_load_lds_dwordx4 v162, s[4:5]
	s_add_u32 m0, s62, 0xc800
	s_add_u32 s4, s56, 0x1c8000
	s_addc_u32 s5, s57, 0
	global_load_lds_dwordx4 v162, s[4:5]
	s_add_u32 m0, s62, 0xd800
	s_add_u32 s4, s56, 0x23a000
	s_addc_u32 s5, s57, 0
	global_load_lds_dwordx4 v162, s[4:5]
	s_add_u32 m0, s62, 0xe800
	s_add_u32 s4, s56, 0x2ac000
	s_addc_u32 s5, s57, 0
	global_load_lds_dwordx4 v162, s[4:5]
	s_add_u32 m0, s62, 0xf800
	s_add_u32 s4, s56, 0x31e000
	s_addc_u32 s5, s57, 0
	global_load_lds_dwordx4 v162, s[4:5]
	s_cmp_gt_u32 s70, 1
	s_cbranch_scc1 .Lg2_up_nodma_1
	s_add_u32 m0, s62, 0x10800
	s_add_u32 s4, s56, 0x390000
	s_addc_u32 s5, s57, 0
	global_load_lds_dwordx4 v162, s[4:5]
.Lg2_up_nodma_1:
	global_load_dwordx4 v[200:203], v160, s[58:59] offset:0
	global_load_dwordx4 v[204:207], v160, s[58:59] offset:1024
	global_load_dwordx4 v[208:211], v161, s[58:59] offset:0
	global_load_dwordx4 v[240:243], v161, s[58:59] offset:1024
	ds_read_b128 v[136:139], v156 offset:0
	ds_read_b128 v[140:143], v156 offset:2048
	ds_read_b128 v[144:147], v156 offset:4096
	ds_read_b128 v[148:151], v156 offset:6144
	ds_read_b128 v[164:167], v156 offset:8192
	ds_read_b128 v[168:171], v156 offset:10240
	ds_read_b128 v[172:175], v156 offset:12288
	ds_read_b128 v[176:179], v156 offset:14336
	s_waitcnt lgkmcnt(4)
	v_mfma_f32_16x16x32_bf16 v[0:3], v[184:187], v[136:139], v[0:3]
	v_mfma_f32_16x16x32_bf16 v[4:7], v[192:195], v[136:139], v[4:7]
	v_mfma_f32_16x16x32_bf16 v[8:11], v[184:187], v[140:143], v[8:11]
	v_mfma_f32_16x16x32_bf16 v[12:15], v[192:195], v[140:143], v[12:15]
	v_mfma_f32_16x16x32_bf16 v[16:19], v[184:187], v[144:147], v[16:19]
	v_mfma_f32_16x16x32_bf16 v[20:23], v[192:195], v[144:147], v[20:23]
	v_mfma_f32_16x16x32_bf16 v[24:27], v[184:187], v[148:151], v[24:27]
	v_mfma_f32_16x16x32_bf16 v[28:31], v[192:195], v[148:151], v[28:31]
	ds_read_b128 v[136:139], v156 offset:16384
	ds_read_b128 v[140:143], v156 offset:18432
	ds_read_b128 v[144:147], v156 offset:20480
	ds_read_b128 v[148:151], v156 offset:22528
	s_waitcnt lgkmcnt(4)
	v_mfma_f32_16x16x32_bf16 v[32:35], v[184:187], v[164:167], v[32:35]
	v_mfma_f32_16x16x32_bf16 v[36:39], v[192:195], v[164:167], v[36:39]
	v_mfma_f32_16x16x32_bf16 v[40:43], v[184:187], v[168:171], v[40:43]
	v_mfma_f32_16x16x32_bf16 v[44:47], v[192:195], v[168:171], v[44:47]
	v_mfma_f32_16x16x32_bf16 v[48:51], v[184:187], v[172:175], v[48:51]
	v_mfma_f32_16x16x32_bf16 v[52:55], v[192:195], v[172:175], v[52:55]
	v_mfma_f32_16x16x32_bf16 v[56:59], v[184:187], v[176:179], v[56:59]
	v_mfma_f32_16x16x32_bf16 v[60:63], v[192:195], v[176:179], v[60:63]
	ds_read_b128 v[164:167], v156 offset:24576
	ds_read_b128 v[168:171], v156 offset:26624
	ds_read_b128 v[172:175], v156 offset:28672
	ds_read_b128 v[176:179], v156 offset:30720
	ds_read_b128 v[180:183], v156 offset:32768
	s_waitcnt lgkmcnt(5)
	v_mfma_f32_16x16x32_bf16 v[64:67], v[184:187], v[136:139], v[64:67]
	v_mfma_f32_16x16x32_bf16 v[68:71], v[192:195], v[136:139], v[68:71]
	v_mfma_f32_16x16x32_bf16 v[72:75], v[184:187], v[140:143], v[72:75]
	v_mfma_f32_16x16x32_bf16 v[76:79], v[192:195], v[140:143], v[76:79]
	v_mfma_f32_16x16x32_bf16 v[80:83], v[184:187], v[144:147], v[80:83]
	v_mfma_f32_16x16x32_bf16 v[84:87], v[192:195], v[144:147], v[84:87]
	v_mfma_f32_16x16x32_bf16 v[88:91], v[184:187], v[148:151], v[88:91]
	v_mfma_f32_16x16x32_bf16 v[92:95], v[192:195], v[148:151], v[92:95]
	ds_read_b128 v[136:139], v157 offset:0
	ds_read_b128 v[140:143], v157 offset:2048
	ds_read_b128 v[144:147], v157 offset:4096
	ds_read_b128 v[148:151], v157 offset:6144
	s_waitcnt lgkmcnt(4)
	v_mfma_f32_16x16x32_bf16 v[96:99], v[184:187], v[164:167], v[96:99]
	v_mfma_f32_16x16x32_bf16 v[100:103], v[192:195], v[164:167], v[100:103]
	v_mfma_f32_16x16x32_bf16 v[104:107], v[184:187], v[168:171], v[104:107]
	v_mfma_f32_16x16x32_bf16 v[108:111], v[192:195], v[168:171], v[108:111]
	v_mfma_f32_16x16x32_bf16 v[112:115], v[184:187], v[172:175], v[112:115]
	v_mfma_f32_16x16x32_bf16 v[116:119], v[192:195], v[172:175], v[116:119]
	v_mfma_f32_16x16x32_bf16 v[120:123], v[184:187], v[176:179], v[120:123]
	v_mfma_f32_16x16x32_bf16 v[124:127], v[192:195], v[176:179], v[124:127]
	v_mfma_f32_16x16x32_bf16 v[128:131], v[184:187], v[180:183], v[128:131]
	v_mfma_f32_16x16x32_bf16 v[132:135], v[192:195], v[180:183], v[132:135]
	ds_read_b128 v[164:167], v157 offset:8192
	ds_read_b128 v[168:171], v157 offset:10240
	ds_read_b128 v[172:175], v157 offset:12288
	ds_read_b128 v[176:179], v157 offset:14336
	s_waitcnt lgkmcnt(4)
	v_mfma_f32_16x16x32_bf16 v[0:3], v[188:191], v[136:139], v[0:3]
	v_mfma_f32_16x16x32_bf16 v[4:7], v[196:199], v[136:139], v[4:7]
	v_mfma_f32_16x16x32_bf16 v[8:11], v[188:191], v[140:143], v[8:11]
	v_mfma_f32_16x16x32_bf16 v[12:15], v[196:199], v[140:143], v[12:15]
	v_mfma_f32_16x16x32_bf16 v[16:19], v[188:191], v[144:147], v[16:19]
	v_mfma_f32_16x16x32_bf16 v[20:23], v[196:199], v[144:147], v[20:23]
	v_mfma_f32_16x16x32_bf16 v[24:27], v[188:191], v[148:151], v[24:27]
	v_mfma_f32_16x16x32_bf16 v[28:31], v[196:199], v[148:151], v[28:31]
	ds_read_b128 v[136:139], v157 offset:16384
	ds_read_b128 v[140:143], v157 offset:18432
	ds_read_b128 v[144:147], v157 offset:20480
	ds_read_b128 v[148:151], v157 offset:22528
	s_waitcnt lgkmcnt(4)
	v_mfma_f32_16x16x32_bf16 v[32:35], v[188:191], v[164:167], v[32:35]
	v_mfma_f32_16x16x32_bf16 v[36:39], v[196:199], v[164:167], v[36:39]
	v_mfma_f32_16x16x32_bf16 v[40:43], v[188:191], v[168:171], v[40:43]
	v_mfma_f32_16x16x32_bf16 v[44:47], v[196:199], v[168:171], v[44:47]
	v_mfma_f32_16x16x32_bf16 v[48:51], v[188:191], v[172:175], v[48:51]
	v_mfma_f32_16x16x32_bf16 v[52:55], v[196:199], v[172:175], v[52:55]
	v_mfma_f32_16x16x32_bf16 v[56:59], v[188:191], v[176:179], v[56:59]
	v_mfma_f32_16x16x32_bf16 v[60:63], v[196:199], v[176:179], v[60:63]
	ds_read_b128 v[164:167], v157 offset:24576
	ds_read_b128 v[168:171], v157 offset:26624
	ds_read_b128 v[172:175], v157 offset:28672
	ds_read_b128 v[176:179], v157 offset:30720
	ds_read_b128 v[180:183], v157 offset:32768
	s_waitcnt lgkmcnt(5)
	v_mfma_f32_16x16x32_bf16 v[64:67], v[188:191], v[136:139], v[64:67]
	v_mfma_f32_16x16x32_bf16 v[68:71], v[196:199], v[136:139], v[68:71]
	v_mfma_f32_16x16x32_bf16 v[72:75], v[188:191], v[140:143], v[72:75]
	v_mfma_f32_16x16x32_bf16 v[76:79], v[196:199], v[140:143], v[76:79]
	v_mfma_f32_16x16x32_bf16 v[80:83], v[188:191], v[144:147], v[80:83]
	v_mfma_f32_16x16x32_bf16 v[84:87], v[196:199], v[144:147], v[84:87]
	v_mfma_f32_16x16x32_bf16 v[88:91], v[188:191], v[148:151], v[88:91]
	v_mfma_f32_16x16x32_bf16 v[92:95], v[196:199], v[148:151], v[92:95]
	s_waitcnt lgkmcnt(0)
	v_mfma_f32_16x16x32_bf16 v[96:99], v[188:191], v[164:167], v[96:99]
	v_mfma_f32_16x16x32_bf16 v[100:103], v[196:199], v[164:167], v[100:103]
	v_mfma_f32_16x16x32_bf16 v[104:107], v[188:191], v[168:171], v[104:107]
	v_mfma_f32_16x16x32_bf16 v[108:111], v[196:199], v[168:171], v[108:111]
	v_mfma_f32_16x16x32_bf16 v[112:115], v[188:191], v[172:175], v[112:115]
	v_mfma_f32_16x16x32_bf16 v[116:119], v[196:199], v[172:175], v[116:119]
	v_mfma_f32_16x16x32_bf16 v[120:123], v[188:191], v[176:179], v[120:123]
	v_mfma_f32_16x16x32_bf16 v[124:127], v[196:199], v[176:179], v[124:127]
	v_mfma_f32_16x16x32_bf16 v[128:131], v[188:191], v[180:183], v[128:131]
	v_mfma_f32_16x16x32_bf16 v[132:135], v[196:199], v[180:183], v[132:135]
	s_waitcnt vmcnt(0)
	s_barrier
	s_cmp_ge_u32 s63, 2
	s_cbranch_scc1 .Lg2_up_noissue17
	s_add_u32 s56, s56, 0x80
	s_addc_u32 s57, s57, 0
	s_add_u32 s58, s58, 0x800
	s_addc_u32 s59, s59, 0
	s_add_u32 m0, s62, 0x0
	s_add_u32 s4, s56, 0x0
	s_addc_u32 s5, s57, 0
	global_load_lds_dwordx4 v162, s[4:5]
	s_add_u32 m0, s62, 0x1000
	s_add_u32 s4, s56, 0x72000
	s_addc_u32 s5, s57, 0
	global_load_lds_dwordx4 v162, s[4:5]
	s_add_u32 m0, s62, 0x2000
	s_add_u32 s4, s56, 0xe4000
	s_addc_u32 s5, s57, 0
	global_load_lds_dwordx4 v162, s[4:5]
	s_add_u32 m0, s62, 0x3000
	s_add_u32 s4, s56, 0x156000
	s_addc_u32 s5, s57, 0
	global_load_lds_dwordx4 v162, s[4:5]
	s_add_u32 m0, s62, 0x4000
	s_add_u32 s4, s56, 0x1c8000
	s_addc_u32 s5, s57, 0
	global_load_lds_dwordx4 v162, s[4:5]
	s_add_u32 m0, s62, 0x5000
	s_add_u32 s4, s56, 0x23a000
	s_addc_u32 s5, s57, 0
	global_load_lds_dwordx4 v162, s[4:5]
	s_add_u32 m0, s62, 0x6000
	s_add_u32 s4, s56, 0x2ac000
	s_addc_u32 s5, s57, 0
	global_load_lds_dwordx4 v162, s[4:5]
	s_add_u32 m0, s62, 0x7000
	s_add_u32 s4, s56, 0x31e000
	s_addc_u32 s5, s57, 0
	global_load_lds_dwordx4 v162, s[4:5]
	s_cmp_gt_u32 s70, 1
	s_cbranch_scc1 .Lg2_up_nodma_2
	s_add_u32 m0, s62, 0x8000
	s_add_u32 s4, s56, 0x390000
	s_addc_u32 s5, s57, 0
	global_load_lds_dwordx4 v162, s[4:5]

.Lg2_up_noissue17:
	ds_read_b128 v[136:139], v158 offset:0
	ds_read_b128 v[140:143], v158 offset:2048
	ds_read_b128 v[144:147], v158 offset:4096
	ds_read_b128 v[148:151], v158 offset:6144
	ds_read_b128 v[164:167], v158 offset:8192
	ds_read_b128 v[168:171], v158 offset:10240
	ds_read_b128 v[172:175], v158 offset:12288
	ds_read_b128 v[176:179], v158 offset:14336
	s_waitcnt lgkmcnt(4)
	v_mfma_f32_16x16x32_bf16 v[0:3], v[200:203], v[136:139], v[0:3]
	v_mfma_f32_16x16x32_bf16 v[4:7], v[208:211], v[136:139], v[4:7]
	v_mfma_f32_16x16x32_bf16 v[8:11], v[200:203], v[140:143], v[8:11]
	v_mfma_f32_16x16x32_bf16 v[12:15], v[208:211], v[140:143], v[12:15]
	v_mfma_f32_16x16x32_bf16 v[16:19], v[200:203], v[144:147], v[16:19]
	v_mfma_f32_16x16x32_bf16 v[20:23], v[208:211], v[144:147], v[20:23]
	v_mfma_f32_16x16x32_bf16 v[24:27], v[200:203], v[148:151], v[24:27]
	v_mfma_f32_16x16x32_bf16 v[28:31], v[208:211], v[148:151], v[28:31]
	ds_read_b128 v[136:139], v158 offset:16384
	ds_read_b128 v[140:143], v158 offset:18432
	ds_read_b128 v[144:147], v158 offset:20480
	ds_read_b128 v[148:151], v158 offset:22528
	s_waitcnt lgkmcnt(4)
	v_mfma_f32_16x16x32_bf16 v[32:35], v[200:203], v[164:167], v[32:35]
	v_mfma_f32_16x16x32_bf16 v[36:39], v[208:211], v[164:167], v[36:39]
	v_mfma_f32_16x16x32_bf16 v[40:43], v[200:203], v[168:171], v[40:43]
	v_mfma_f32_16x16x32_bf16 v[44:47], v[208:211], v[168:171], v[44:47]
	v_mfma_f32_16x16x32_bf16 v[48:51], v[200:203], v[172:175], v[48:51]
	v_mfma_f32_16x16x32_bf16 v[52:55], v[208:211], v[172:175], v[52:55]
	v_mfma_f32_16x16x32_bf16 v[56:59], v[200:203], v[176:179], v[56:59]
	v_mfma_f32_16x16x32_bf16 v[60:63], v[208:211], v[176:179], v[60:63]
	ds_read_b128 v[164:167], v158 offset:24576
	ds_read_b128 v[168:171], v158 offset:26624
	ds_read_b128 v[172:175], v158 offset:28672
	ds_read_b128 v[176:179], v158 offset:30720
	ds_read_b128 v[180:183], v158 offset:32768
	s_waitcnt lgkmcnt(5)
	v_mfma_f32_16x16x32_bf16 v[64:67], v[200:203], v[136:139], v[64:67]
	v_mfma_f32_16x16x32_bf16 v[68:71], v[208:211], v[136:139], v[68:71]
	v_mfma_f32_16x16x32_bf16 v[72:75], v[200:203], v[140:143], v[72:75]
	v_mfma_f32_16x16x32_bf16 v[76:79], v[208:211], v[140:143], v[76:79]
	v_mfma_f32_16x16x32_bf16 v[80:83], v[200:203], v[144:147], v[80:83]
	v_mfma_f32_16x16x32_bf16 v[84:87], v[208:211], v[144:147], v[84:87]
	v_mfma_f32_16x16x32_bf16 v[88:91], v[200:203], v[148:151], v[88:91]
	v_mfma_f32_16x16x32_bf16 v[92:95], v[208:211], v[148:151], v[92:95]
	ds_read_b128 v[136:139], v159 offset:0
	ds_read_b128 v[140:143], v159 offset:2048
	ds_read_b128 v[144:147], v159 offset:4096
	ds_read_b128 v[148:151], v159 offset:6144
	s_waitcnt lgkmcnt(4)
	v_mfma_f32_16x16x32_bf16 v[96:99], v[200:203], v[164:167], v[96:99]
	v_mfma_f32_16x16x32_bf16 v[100:103], v[208:211], v[164:167], v[100:103]
	v_mfma_f32_16x16x32_bf16 v[104:107], v[200:203], v[168:171], v[104:107]
	v_mfma_f32_16x16x32_bf16 v[108:111], v[208:211], v[168:171], v[108:111]
	v_mfma_f32_16x16x32_bf16 v[112:115], v[200:203], v[172:175], v[112:115]
	v_mfma_f32_16x16x32_bf16 v[116:119], v[208:211], v[172:175], v[116:119]
	v_mfma_f32_16x16x32_bf16 v[120:123], v[200:203], v[176:179], v[120:123]
	v_mfma_f32_16x16x32_bf16 v[124:127], v[208:211], v[176:179], v[124:127]
	v_mfma_f32_16x16x32_bf16 v[128:131], v[200:203], v[180:183], v[128:131]
	v_mfma_f32_16x16x32_bf16 v[132:135], v[208:211], v[180:183], v[132:135]
	ds_read_b128 v[164:167], v159 offset:8192
	ds_read_b128 v[168:171], v159 offset:10240
	ds_read_b128 v[172:175], v159 offset:12288
	ds_read_b128 v[176:179], v159 offset:14336
	s_waitcnt lgkmcnt(4)
	v_mfma_f32_16x16x32_bf16 v[0:3], v[204:207], v[136:139], v[0:3]
	v_mfma_f32_16x16x32_bf16 v[4:7], v[240:243], v[136:139], v[4:7]
	v_mfma_f32_16x16x32_bf16 v[8:11], v[204:207], v[140:143], v[8:11]
	v_mfma_f32_16x16x32_bf16 v[12:15], v[240:243], v[140:143], v[12:15]
	v_mfma_f32_16x16x32_bf16 v[16:19], v[204:207], v[144:147], v[16:19]
	v_mfma_f32_16x16x32_bf16 v[20:23], v[240:243], v[144:147], v[20:23]
	v_mfma_f32_16x16x32_bf16 v[24:27], v[204:207], v[148:151], v[24:27]
	v_mfma_f32_16x16x32_bf16 v[28:31], v[240:243], v[148:151], v[28:31]
	ds_read_b128 v[136:139], v159 offset:16384
	ds_read_b128 v[140:143], v159 offset:18432
	ds_read_b128 v[144:147], v159 offset:20480
	ds_read_b128 v[148:151], v159 offset:22528
	s_waitcnt lgkmcnt(4)
	v_mfma_f32_16x16x32_bf16 v[32:35], v[204:207], v[164:167], v[32:35]
	v_mfma_f32_16x16x32_bf16 v[36:39], v[240:243], v[164:167], v[36:39]
	v_mfma_f32_16x16x32_bf16 v[40:43], v[204:207], v[168:171], v[40:43]
	v_mfma_f32_16x16x32_bf16 v[44:47], v[240:243], v[168:171], v[44:47]
	v_mfma_f32_16x16x32_bf16 v[48:51], v[204:207], v[172:175], v[48:51]
	v_mfma_f32_16x16x32_bf16 v[52:55], v[240:243], v[172:175], v[52:55]
	v_mfma_f32_16x16x32_bf16 v[56:59], v[204:207], v[176:179], v[56:59]
	v_mfma_f32_16x16x32_bf16 v[60:63], v[240:243], v[176:179], v[60:63]
	ds_read_b128 v[164:167], v159 offset:24576
	ds_read_b128 v[168:171], v159 offset:26624
	ds_read_b128 v[172:175], v159 offset:28672
	ds_read_b128 v[176:179], v159 offset:30720
	ds_read_b128 v[180:183], v159 offset:32768
	s_waitcnt lgkmcnt(5)
	v_mfma_f32_16x16x32_bf16 v[64:67], v[204:207], v[136:139], v[64:67]
	v_mfma_f32_16x16x32_bf16 v[68:71], v[240:243], v[136:139], v[68:71]
	v_mfma_f32_16x16x32_bf16 v[72:75], v[204:207], v[140:143], v[72:75]
	v_mfma_f32_16x16x32_bf16 v[76:79], v[240:243], v[140:143], v[76:79]
	v_mfma_f32_16x16x32_bf16 v[80:83], v[204:207], v[144:147], v[80:83]
	v_mfma_f32_16x16x32_bf16 v[84:87], v[240:243], v[144:147], v[84:87]
	v_mfma_f32_16x16x32_bf16 v[88:91], v[204:207], v[148:151], v[88:91]
	v_mfma_f32_16x16x32_bf16 v[92:95], v[240:243], v[148:151], v[92:95]
	s_waitcnt lgkmcnt(0)
	v_mfma_f32_16x16x32_bf16 v[96:99], v[204:207], v[164:167], v[96:99]
	v_mfma_f32_16x16x32_bf16 v[100:103], v[240:243], v[164:167], v[100:103]
	v_mfma_f32_16x16x32_bf16 v[104:107], v[204:207], v[168:171], v[104:107]
	v_mfma_f32_16x16x32_bf16 v[108:111], v[240:243], v[168:171], v[108:111]
	v_mfma_f32_16x16x32_bf16 v[112:115], v[204:207], v[172:175], v[112:115]
	v_mfma_f32_16x16x32_bf16 v[116:119], v[240:243], v[172:175], v[116:119]
	v_mfma_f32_16x16x32_bf16 v[120:123], v[204:207], v[176:179], v[120:123]
	v_mfma_f32_16x16x32_bf16 v[124:127], v[240:243], v[176:179], v[124:127]
	v_mfma_f32_16x16x32_bf16 v[128:131], v[204:207], v[180:183], v[128:131]
	v_mfma_f32_16x16x32_bf16 v[132:135], v[240:243], v[180:183], v[132:135]
	s_add_i32 s63, s63, 2
	s_cmp_lt_u32 s63, 4
	s_cbranch_scc1 .Lg2_up_loop17
	s_branch .Lg2_up_episel
.Lg2_up_k16:
	s_add_u32 m0, s62, 0x0
	s_add_u32 s4, s56, 0x0
	s_addc_u32 s5, s57, 0
	global_load_lds_dwordx4 v162, s[4:5]
	s_add_u32 m0, s62, 0x1000
	s_add_u32 s4, s56, 0x72000
	s_addc_u32 s5, s57, 0
	global_load_lds_dwordx4 v162, s[4:5]
	s_add_u32 m0, s62, 0x2000
	s_add_u32 s4, s56, 0xe4000
	s_addc_u32 s5, s57, 0
	global_load_lds_dwordx4 v162, s[4:5]
	s_add_u32 m0, s62, 0x3000
	s_add_u32 s4, s56, 0x156000
	s_addc_u32 s5, s57, 0
	global_load_lds_dwordx4 v162, s[4:5]
	s_add_u32 m0, s62, 0x4000
	s_add_u32 s4, s56, 0x1c8000
	s_addc_u32 s5, s57, 0
	global_load_lds_dwordx4 v162, s[4:5]
	s_add_u32 m0, s62, 0x5000
	s_add_u32 s4, s56, 0x23a000
	s_addc_u32 s5, s57, 0
	global_load_lds_dwordx4 v162, s[4:5]
	s_add_u32 m0, s62, 0x6000
	s_add_u32 s4, s56, 0x2ac000
	s_addc_u32 s5, s57, 0
	global_load_lds_dwordx4 v162, s[4:5]
	s_add_u32 m0, s62, 0x7000
	s_add_u32 s4, s56, 0x31e000
	s_addc_u32 s5, s57, 0
	global_load_lds_dwordx4 v162, s[4:5]
	global_load_dwordx4 v[184:187], v160, s[58:59] offset:0
	global_load_dwordx4 v[188:191], v160, s[58:59] offset:1024
	global_load_dwordx4 v[192:195], v161, s[58:59] offset:0
	global_load_dwordx4 v[196:199], v161, s[58:59] offset:1024
	v_mov_b32_e32 v0, 0
	v_mov_b32_e32 v1, 0
	v_mov_b32_e32 v2, 0
	v_mov_b32_e32 v3, 0
	v_mov_b32_e32 v4, 0
	v_mov_b32_e32 v5, 0
	v_mov_b32_e32 v6, 0
	v_mov_b32_e32 v7, 0
	v_mov_b32_e32 v8, 0
	v_mov_b32_e32 v9, 0
	v_mov_b32_e32 v10, 0
	v_mov_b32_e32 v11, 0
	v_mov_b32_e32 v12, 0
	v_mov_b32_e32 v13, 0
	v_mov_b32_e32 v14, 0
	v_mov_b32_e32 v15, 0
	v_mov_b32_e32 v16, 0
	v_mov_b32_e32 v17, 0
	v_mov_b32_e32 v18, 0
	v_mov_b32_e32 v19, 0
	v_mov_b32_e32 v20, 0
	v_mov_b32_e32 v21, 0
	v_mov_b32_e32 v22, 0
	v_mov_b32_e32 v23, 0
	v_mov_b32_e32 v24, 0
	v_mov_b32_e32 v25, 0
	v_mov_b32_e32 v26, 0
	v_mov_b32_e32 v27, 0
	v_mov_b32_e32 v28, 0
	v_mov_b32_e32 v29, 0
	v_mov_b32_e32 v30, 0
	v_mov_b32_e32 v31, 0
	v_mov_b32_e32 v32, 0
	v_mov_b32_e32 v33, 0
	v_mov_b32_e32 v34, 0
	v_mov_b32_e32 v35, 0
	v_mov_b32_e32 v36, 0
	v_mov_b32_e32 v37, 0
	v_mov_b32_e32 v38, 0
	v_mov_b32_e32 v39, 0
	v_mov_b32_e32 v40, 0
	v_mov_b32_e32 v41, 0
	v_mov_b32_e32 v42, 0
	v_mov_b32_e32 v43, 0
	v_mov_b32_e32 v44, 0
	v_mov_b32_e32 v45, 0
	v_mov_b32_e32 v46, 0
	v_mov_b32_e32 v47, 0
	v_mov_b32_e32 v48, 0
	v_mov_b32_e32 v49, 0
	v_mov_b32_e32 v50, 0
	v_mov_b32_e32 v51, 0
	v_mov_b32_e32 v52, 0
	v_mov_b32_e32 v53, 0
	v_mov_b32_e32 v54, 0
	v_mov_b32_e32 v55, 0
	v_mov_b32_e32 v56, 0
	v_mov_b32_e32 v57, 0
	v_mov_b32_e32 v58, 0
	v_mov_b32_e32 v59, 0
	v_mov_b32_e32 v60, 0
	v_mov_b32_e32 v61, 0
	v_mov_b32_e32 v62, 0
	v_mov_b32_e32 v63, 0
	v_mov_b32_e32 v64, 0
	v_mov_b32_e32 v65, 0
	v_mov_b32_e32 v66, 0
	v_mov_b32_e32 v67, 0
	v_mov_b32_e32 v68, 0
	v_mov_b32_e32 v69, 0
	v_mov_b32_e32 v70, 0
	v_mov_b32_e32 v71, 0
	v_mov_b32_e32 v72, 0
	v_mov_b32_e32 v73, 0
	v_mov_b32_e32 v74, 0
	v_mov_b32_e32 v75, 0
	v_mov_b32_e32 v76, 0
	v_mov_b32_e32 v77, 0
	v_mov_b32_e32 v78, 0
	v_mov_b32_e32 v79, 0
	v_mov_b32_e32 v80, 0
	v_mov_b32_e32 v81, 0
	v_mov_b32_e32 v82, 0
	v_mov_b32_e32 v83, 0
	v_mov_b32_e32 v84, 0
	v_mov_b32_e32 v85, 0
	v_mov_b32_e32 v86, 0
	v_mov_b32_e32 v87, 0
	v_mov_b32_e32 v88, 0
	v_mov_b32_e32 v89, 0
	v_mov_b32_e32 v90, 0
	v_mov_b32_e32 v91, 0
	v_mov_b32_e32 v92, 0
	v_mov_b32_e32 v93, 0
	v_mov_b32_e32 v94, 0
	v_mov_b32_e32 v95, 0
	v_mov_b32_e32 v96, 0
	v_mov_b32_e32 v97, 0
	v_mov_b32_e32 v98, 0
	v_mov_b32_e32 v99, 0
	v_mov_b32_e32 v100, 0
	v_mov_b32_e32 v101, 0
	v_mov_b32_e32 v102, 0
	v_mov_b32_e32 v103, 0
	v_mov_b32_e32 v104, 0
	v_mov_b32_e32 v105, 0
	v_mov_b32_e32 v106, 0
	v_mov_b32_e32 v107, 0
	v_mov_b32_e32 v108, 0
	v_mov_b32_e32 v109, 0
	v_mov_b32_e32 v110, 0
	v_mov_b32_e32 v111, 0
	v_mov_b32_e32 v112, 0
	v_mov_b32_e32 v113, 0
	v_mov_b32_e32 v114, 0
	v_mov_b32_e32 v115, 0
	v_mov_b32_e32 v116, 0
	v_mov_b32_e32 v117, 0
	v_mov_b32_e32 v118, 0
	v_mov_b32_e32 v119, 0
	v_mov_b32_e32 v120, 0
	v_mov_b32_e32 v121, 0
	v_mov_b32_e32 v122, 0
	v_mov_b32_e32 v123, 0
	v_mov_b32_e32 v124, 0
	v_mov_b32_e32 v125, 0
	v_mov_b32_e32 v126, 0
	v_mov_b32_e32 v127, 0
	s_mov_b32 s63, 0
.Lg2_up_loop16:
	s_waitcnt vmcnt(0)
	s_barrier
	s_add_u32 s56, s56, 0x80
	s_addc_u32 s57, s57, 0
	s_add_u32 s58, s58, 0x800
	s_addc_u32 s59, s59, 0
	s_add_u32 m0, s62, 0x8800
	s_add_u32 s4, s56, 0x0
	s_addc_u32 s5, s57, 0
	global_load_lds_dwordx4 v162, s[4:5]
	s_add_u32 m0, s62, 0x9800
	s_add_u32 s4, s56, 0x72000
	s_addc_u32 s5, s57, 0
	global_load_lds_dwordx4 v162, s[4:5]
	s_add_u32 m0, s62, 0xa800
	s_add_u32 s4, s56, 0xe4000
	s_addc_u32 s5, s57, 0
	global_load_lds_dwordx4 v162, s[4:5]
	s_add_u32 m0, s62, 0xb800
	s_add_u32 s4, s56, 0x156000
	s_addc_u32 s5, s57, 0
	global_load_lds_dwordx4 v162, s[4:5]
	s_add_u32 m0, s62, 0xc800
	s_add_u32 s4, s56, 0x1c8000
	s_addc_u32 s5, s57, 0
	global_load_lds_dwordx4 v162, s[4:5]
	s_add_u32 m0, s62, 0xd800
	s_add_u32 s4, s56, 0x23a000
	s_addc_u32 s5, s57, 0
	global_load_lds_dwordx4 v162, s[4:5]
	s_add_u32 m0, s62, 0xe800
	s_add_u32 s4, s56, 0x2ac000
	s_addc_u32 s5, s57, 0
	global_load_lds_dwordx4 v162, s[4:5]
	s_add_u32 m0, s62, 0xf800
	s_add_u32 s4, s56, 0x31e000
	s_addc_u32 s5, s57, 0
	global_load_lds_dwordx4 v162, s[4:5]
	global_load_dwordx4 v[200:203], v160, s[58:59] offset:0
	global_load_dwordx4 v[204:207], v160, s[58:59] offset:1024
	global_load_dwordx4 v[208:211], v161, s[58:59] offset:0
	global_load_dwordx4 v[240:243], v161, s[58:59] offset:1024
	ds_read_b128 v[136:139], v156 offset:0
	ds_read_b128 v[140:143], v156 offset:2048
	ds_read_b128 v[144:147], v156 offset:4096
	ds_read_b128 v[148:151], v156 offset:6144
	ds_read_b128 v[164:167], v156 offset:8192
	ds_read_b128 v[168:171], v156 offset:10240
	ds_read_b128 v[172:175], v156 offset:12288
	ds_read_b128 v[176:179], v156 offset:14336
	s_waitcnt lgkmcnt(4)
	v_mfma_f32_16x16x32_bf16 v[0:3], v[184:187], v[136:139], v[0:3]
	v_mfma_f32_16x16x32_bf16 v[4:7], v[192:195], v[136:139], v[4:7]
	v_mfma_f32_16x16x32_bf16 v[8:11], v[184:187], v[140:143], v[8:11]
	v_mfma_f32_16x16x32_bf16 v[12:15], v[192:195], v[140:143], v[12:15]
	v_mfma_f32_16x16x32_bf16 v[16:19], v[184:187], v[144:147], v[16:19]
	v_mfma_f32_16x16x32_bf16 v[20:23], v[192:195], v[144:147], v[20:23]
	v_mfma_f32_16x16x32_bf16 v[24:27], v[184:187], v[148:151], v[24:27]
	v_mfma_f32_16x16x32_bf16 v[28:31], v[192:195], v[148:151], v[28:31]
	ds_read_b128 v[136:139], v156 offset:16384
	ds_read_b128 v[140:143], v156 offset:18432
	ds_read_b128 v[144:147], v156 offset:20480
	ds_read_b128 v[148:151], v156 offset:22528
	s_waitcnt lgkmcnt(4)
	v_mfma_f32_16x16x32_bf16 v[32:35], v[184:187], v[164:167], v[32:35]
	v_mfma_f32_16x16x32_bf16 v[36:39], v[192:195], v[164:167], v[36:39]
	v_mfma_f32_16x16x32_bf16 v[40:43], v[184:187], v[168:171], v[40:43]
	v_mfma_f32_16x16x32_bf16 v[44:47], v[192:195], v[168:171], v[44:47]
	v_mfma_f32_16x16x32_bf16 v[48:51], v[184:187], v[172:175], v[48:51]
	v_mfma_f32_16x16x32_bf16 v[52:55], v[192:195], v[172:175], v[52:55]
	v_mfma_f32_16x16x32_bf16 v[56:59], v[184:187], v[176:179], v[56:59]
	v_mfma_f32_16x16x32_bf16 v[60:63], v[192:195], v[176:179], v[60:63]
	ds_read_b128 v[164:167], v156 offset:24576
	ds_read_b128 v[168:171], v156 offset:26624
	ds_read_b128 v[172:175], v156 offset:28672
	ds_read_b128 v[176:179], v156 offset:30720
	s_waitcnt lgkmcnt(4)
	v_mfma_f32_16x16x32_bf16 v[64:67], v[184:187], v[136:139], v[64:67]
	v_mfma_f32_16x16x32_bf16 v[68:71], v[192:195], v[136:139], v[68:71]
	v_mfma_f32_16x16x32_bf16 v[72:75], v[184:187], v[140:143], v[72:75]
	v_mfma_f32_16x16x32_bf16 v[76:79], v[192:195], v[140:143], v[76:79]
	v_mfma_f32_16x16x32_bf16 v[80:83], v[184:187], v[144:147], v[80:83]
	v_mfma_f32_16x16x32_bf16 v[84:87], v[192:195], v[144:147], v[84:87]
	v_mfma_f32_16x16x32_bf16 v[88:91], v[184:187], v[148:151], v[88:91]
	v_mfma_f32_16x16x32_bf16 v[92:95], v[192:195], v[148:151], v[92:95]
	ds_read_b128 v[136:139], v157 offset:0
	ds_read_b128 v[140:143], v157 offset:2048
	ds_read_b128 v[144:147], v157 offset:4096
	ds_read_b128 v[148:151], v157 offset:6144
	s_waitcnt lgkmcnt(4)
	v_mfma_f32_16x16x32_bf16 v[96:99], v[184:187], v[164:167], v[96:99]
	v_mfma_f32_16x16x32_bf16 v[100:103], v[192:195], v[164:167], v[100:103]
	v_mfma_f32_16x16x32_bf16 v[104:107], v[184:187], v[168:171], v[104:107]
	v_mfma_f32_16x16x32_bf16 v[108:111], v[192:195], v[168:171], v[108:111]
	v_mfma_f32_16x16x32_bf16 v[112:115], v[184:187], v[172:175], v[112:115]
	v_mfma_f32_16x16x32_bf16 v[116:119], v[192:195], v[172:175], v[116:119]
	v_mfma_f32_16x16x32_bf16 v[120:123], v[184:187], v[176:179], v[120:123]
	v_mfma_f32_16x16x32_bf16 v[124:127], v[192:195], v[176:179], v[124:127]
	ds_read_b128 v[164:167], v157 offset:8192
	ds_read_b128 v[168:171], v157 offset:10240
	ds_read_b128 v[172:175], v157 offset:12288
	ds_read_b128 v[176:179], v157 offset:14336
	s_waitcnt lgkmcnt(4)
	v_mfma_f32_16x16x32_bf16 v[0:3], v[188:191], v[136:139], v[0:3]
	v_mfma_f32_16x16x32_bf16 v[4:7], v[196:199], v[136:139], v[4:7]
	v_mfma_f32_16x16x32_bf16 v[8:11], v[188:191], v[140:143], v[8:11]
	v_mfma_f32_16x16x32_bf16 v[12:15], v[196:199], v[140:143], v[12:15]
	v_mfma_f32_16x16x32_bf16 v[16:19], v[188:191], v[144:147], v[16:19]
	v_mfma_f32_16x16x32_bf16 v[20:23], v[196:199], v[144:147], v[20:23]
	v_mfma_f32_16x16x32_bf16 v[24:27], v[188:191], v[148:151], v[24:27]
	v_mfma_f32_16x16x32_bf16 v[28:31], v[196:199], v[148:151], v[28:31]
	ds_read_b128 v[136:139], v157 offset:16384
	ds_read_b128 v[140:143], v157 offset:18432
	ds_read_b128 v[144:147], v157 offset:20480
	ds_read_b128 v[148:151], v157 offset:22528
	s_waitcnt lgkmcnt(4)
	v_mfma_f32_16x16x32_bf16 v[32:35], v[188:191], v[164:167], v[32:35]
	v_mfma_f32_16x16x32_bf16 v[36:39], v[196:199], v[164:167], v[36:39]
	v_mfma_f32_16x16x32_bf16 v[40:43], v[188:191], v[168:171], v[40:43]
	v_mfma_f32_16x16x32_bf16 v[44:47], v[196:199], v[168:171], v[44:47]
	v_mfma_f32_16x16x32_bf16 v[48:51], v[188:191], v[172:175], v[48:51]
	v_mfma_f32_16x16x32_bf16 v[52:55], v[196:199], v[172:175], v[52:55]
	v_mfma_f32_16x16x32_bf16 v[56:59], v[188:191], v[176:179], v[56:59]
	v_mfma_f32_16x16x32_bf16 v[60:63], v[196:199], v[176:179], v[60:63]
	ds_read_b128 v[164:167], v157 offset:24576
	ds_read_b128 v[168:171], v157 offset:26624
	ds_read_b128 v[172:175], v157 offset:28672
	ds_read_b128 v[176:179], v157 offset:30720
	s_waitcnt lgkmcnt(4)
	v_mfma_f32_16x16x32_bf16 v[64:67], v[188:191], v[136:139], v[64:67]
	v_mfma_f32_16x16x32_bf16 v[68:71], v[196:199], v[136:139], v[68:71]
	v_mfma_f32_16x16x32_bf16 v[72:75], v[188:191], v[140:143], v[72:75]
	v_mfma_f32_16x16x32_bf16 v[76:79], v[196:199], v[140:143], v[76:79]
	v_mfma_f32_16x16x32_bf16 v[80:83], v[188:191], v[144:147], v[80:83]
	v_mfma_f32_16x16x32_bf16 v[84:87], v[196:199], v[144:147], v[84:87]
	v_mfma_f32_16x16x32_bf16 v[88:91], v[188:191], v[148:151], v[88:91]
	v_mfma_f32_16x16x32_bf16 v[92:95], v[196:199], v[148:151], v[92:95]
	s_waitcnt lgkmcnt(0)
	v_mfma_f32_16x16x32_bf16 v[96:99], v[188:191], v[164:167], v[96:99]
	v_mfma_f32_16x16x32_bf16 v[100:103], v[196:199], v[164:167], v[100:103]
	v_mfma_f32_16x16x32_bf16 v[104:107], v[188:191], v[168:171], v[104:107]
	v_mfma_f32_16x16x32_bf16 v[108:111], v[196:199], v[168:171], v[108:111]
	v_mfma_f32_16x16x32_bf16 v[112:115], v[188:191], v[172:175], v[112:115]
	v_mfma_f32_16x16x32_bf16 v[116:119], v[196:199], v[172:175], v[116:119]
	v_mfma_f32_16x16x32_bf16 v[120:123], v[188:191], v[176:179], v[120:123]
	v_mfma_f32_16x16x32_bf16 v[124:127], v[196:199], v[176:179], v[124:127]
	s_waitcnt vmcnt(0)
	s_barrier
	s_cmp_ge_u32 s63, 2
	s_cbranch_scc1 .Lg2_up_noissue16
	s_add_u32 s56, s56, 0x80
	s_addc_u32 s57, s57, 0
	s_add_u32 s58, s58, 0x800
	s_addc_u32 s59, s59, 0
	s_add_u32 m0, s62, 0x0
	s_add_u32 s4, s56, 0x0
	s_addc_u32 s5, s57, 0
	global_load_lds_dwordx4 v162, s[4:5]
	s_add_u32 m0, s62, 0x1000
	s_add_u32 s4, s56, 0x72000
	s_addc_u32 s5, s57, 0
	global_load_lds_dwordx4 v162, s[4:5]
	s_add_u32 m0, s62, 0x2000
	s_add_u32 s4, s56, 0xe4000
	s_addc_u32 s5, s57, 0
	global_load_lds_dwordx4 v162, s[4:5]
	s_add_u32 m0, s62, 0x3000
	s_add_u32 s4, s56, 0x156000
	s_addc_u32 s5, s57, 0
	global_load_lds_dwordx4 v162, s[4:5]
	s_add_u32 m0, s62, 0x4000
	s_add_u32 s4, s56, 0x1c8000
	s_addc_u32 s5, s57, 0
	global_load_lds_dwordx4 v162, s[4:5]
	s_add_u32 m0, s62, 0x5000
	s_add_u32 s4, s56, 0x23a000
	s_addc_u32 s5, s57, 0
	global_load_lds_dwordx4 v162, s[4:5]
	s_add_u32 m0, s62, 0x6000
	s_add_u32 s4, s56, 0x2ac000
	s_addc_u32 s5, s57, 0
	global_load_lds_dwordx4 v162, s[4:5]
	s_add_u32 m0, s62, 0x7000
	s_add_u32 s4, s56, 0x31e000
	s_addc_u32 s5, s57, 0
	global_load_lds_dwordx4 v162, s[4:5]
	global_load_dwordx4 v[184:187], v160, s[58:59] offset:0
	global_load_dwordx4 v[188:191], v160, s[58:59] offset:1024
	global_load_dwordx4 v[192:195], v161, s[58:59] offset:0
	global_load_dwordx4 v[196:199], v161, s[58:59] offset:1024
.Lg2_up_noissue16:
	ds_read_b128 v[136:139], v158 offset:0
	ds_read_b128 v[140:143], v158 offset:2048
	ds_read_b128 v[144:147], v158 offset:4096
	ds_read_b128 v[148:151], v158 offset:6144
	ds_read_b128 v[164:167], v158 offset:8192
	ds_read_b128 v[168:171], v158 offset:10240
	ds_read_b128 v[172:175], v158 offset:12288
	ds_read_b128 v[176:179], v158 offset:14336
	s_waitcnt lgkmcnt(4)
	v_mfma_f32_16x16x32_bf16 v[0:3], v[200:203], v[136:139], v[0:3]
	v_mfma_f32_16x16x32_bf16 v[4:7], v[208:211], v[136:139], v[4:7]
	v_mfma_f32_16x16x32_bf16 v[8:11], v[200:203], v[140:143], v[8:11]
	v_mfma_f32_16x16x32_bf16 v[12:15], v[208:211], v[140:143], v[12:15]
	v_mfma_f32_16x16x32_bf16 v[16:19], v[200:203], v[144:147], v[16:19]
	v_mfma_f32_16x16x32_bf16 v[20:23], v[208:211], v[144:147], v[20:23]
	v_mfma_f32_16x16x32_bf16 v[24:27], v[200:203], v[148:151], v[24:27]
	v_mfma_f32_16x16x32_bf16 v[28:31], v[208:211], v[148:151], v[28:31]
	ds_read_b128 v[136:139], v158 offset:16384
	ds_read_b128 v[140:143], v158 offset:18432
	ds_read_b128 v[144:147], v158 offset:20480
	ds_read_b128 v[148:151], v158 offset:22528
	s_waitcnt lgkmcnt(4)
	v_mfma_f32_16x16x32_bf16 v[32:35], v[200:203], v[164:167], v[32:35]
	v_mfma_f32_16x16x32_bf16 v[36:39], v[208:211], v[164:167], v[36:39]
	v_mfma_f32_16x16x32_bf16 v[40:43], v[200:203], v[168:171], v[40:43]
	v_mfma_f32_16x16x32_bf16 v[44:47], v[208:211], v[168:171], v[44:47]
	v_mfma_f32_16x16x32_bf16 v[48:51], v[200:203], v[172:175], v[48:51]
	v_mfma_f32_16x16x32_bf16 v[52:55], v[208:211], v[172:175], v[52:55]
	v_mfma_f32_16x16x32_bf16 v[56:59], v[200:203], v[176:179], v[56:59]
	v_mfma_f32_16x16x32_bf16 v[60:63], v[208:211], v[176:179], v[60:63]
	ds_read_b128 v[164:167], v158 offset:24576
	ds_read_b128 v[168:171], v158 offset:26624
	ds_read_b128 v[172:175], v158 offset:28672
	ds_read_b128 v[176:179], v158 offset:30720
	s_waitcnt lgkmcnt(4)
	v_mfma_f32_16x16x32_bf16 v[64:67], v[200:203], v[136:139], v[64:67]
	v_mfma_f32_16x16x32_bf16 v[68:71], v[208:211], v[136:139], v[68:71]
	v_mfma_f32_16x16x32_bf16 v[72:75], v[200:203], v[140:143], v[72:75]
	v_mfma_f32_16x16x32_bf16 v[76:79], v[208:211], v[140:143], v[76:79]
	v_mfma_f32_16x16x32_bf16 v[80:83], v[200:203], v[144:147], v[80:83]
	v_mfma_f32_16x16x32_bf16 v[84:87], v[208:211], v[144:147], v[84:87]
	v_mfma_f32_16x16x32_bf16 v[88:91], v[200:203], v[148:151], v[88:91]
	v_mfma_f32_16x16x32_bf16 v[92:95], v[208:211], v[148:151], v[92:95]
	ds_read_b128 v[136:139], v159 offset:0
	ds_read_b128 v[140:143], v159 offset:2048
	ds_read_b128 v[144:147], v159 offset:4096
	ds_read_b128 v[148:151], v159 offset:6144
	s_waitcnt lgkmcnt(4)
	v_mfma_f32_16x16x32_bf16 v[96:99], v[200:203], v[164:167], v[96:99]
	v_mfma_f32_16x16x32_bf16 v[100:103], v[208:211], v[164:167], v[100:103]
	v_mfma_f32_16x16x32_bf16 v[104:107], v[200:203], v[168:171], v[104:107]
	v_mfma_f32_16x16x32_bf16 v[108:111], v[208:211], v[168:171], v[108:111]
	v_mfma_f32_16x16x32_bf16 v[112:115], v[200:203], v[172:175], v[112:115]
	v_mfma_f32_16x16x32_bf16 v[116:119], v[208:211], v[172:175], v[116:119]
	v_mfma_f32_16x16x32_bf16 v[120:123], v[200:203], v[176:179], v[120:123]
	v_mfma_f32_16x16x32_bf16 v[124:127], v[208:211], v[176:179], v[124:127]
	ds_read_b128 v[164:167], v159 offset:8192
	ds_read_b128 v[168:171], v159 offset:10240
	ds_read_b128 v[172:175], v159 offset:12288
	ds_read_b128 v[176:179], v159 offset:14336
	s_waitcnt lgkmcnt(4)
	v_mfma_f32_16x16x32_bf16 v[0:3], v[204:207], v[136:139], v[0:3]
	v_mfma_f32_16x16x32_bf16 v[4:7], v[240:243], v[136:139], v[4:7]
	v_mfma_f32_16x16x32_bf16 v[8:11], v[204:207], v[140:143], v[8:11]
	v_mfma_f32_16x16x32_bf16 v[12:15], v[240:243], v[140:143], v[12:15]
	v_mfma_f32_16x16x32_bf16 v[16:19], v[204:207], v[144:147], v[16:19]
	v_mfma_f32_16x16x32_bf16 v[20:23], v[240:243], v[144:147], v[20:23]
	v_mfma_f32_16x16x32_bf16 v[24:27], v[204:207], v[148:151], v[24:27]
	v_mfma_f32_16x16x32_bf16 v[28:31], v[240:243], v[148:151], v[28:31]
	ds_read_b128 v[136:139], v159 offset:16384
	ds_read_b128 v[140:143], v159 offset:18432
	ds_read_b128 v[144:147], v159 offset:20480
	ds_read_b128 v[148:151], v159 offset:22528
	s_waitcnt lgkmcnt(4)
	v_mfma_f32_16x16x32_bf16 v[32:35], v[204:207], v[164:167], v[32:35]
	v_mfma_f32_16x16x32_bf16 v[36:39], v[240:243], v[164:167], v[36:39]
	v_mfma_f32_16x16x32_bf16 v[40:43], v[204:207], v[168:171], v[40:43]
	v_mfma_f32_16x16x32_bf16 v[44:47], v[240:243], v[168:171], v[44:47]
	v_mfma_f32_16x16x32_bf16 v[48:51], v[204:207], v[172:175], v[48:51]
	v_mfma_f32_16x16x32_bf16 v[52:55], v[240:243], v[172:175], v[52:55]
	v_mfma_f32_16x16x32_bf16 v[56:59], v[204:207], v[176:179], v[56:59]
	v_mfma_f32_16x16x32_bf16 v[60:63], v[240:243], v[176:179], v[60:63]
	ds_read_b128 v[164:167], v159 offset:24576
	ds_read_b128 v[168:171], v159 offset:26624
	ds_read_b128 v[172:175], v159 offset:28672
	ds_read_b128 v[176:179], v159 offset:30720
	s_waitcnt lgkmcnt(4)
	v_mfma_f32_16x16x32_bf16 v[64:67], v[204:207], v[136:139], v[64:67]
	v_mfma_f32_16x16x32_bf16 v[68:71], v[240:243], v[136:139], v[68:71]
	v_mfma_f32_16x16x32_bf16 v[72:75], v[204:207], v[140:143], v[72:75]
	v_mfma_f32_16x16x32_bf16 v[76:79], v[240:243], v[140:143], v[76:79]
	v_mfma_f32_16x16x32_bf16 v[80:83], v[204:207], v[144:147], v[80:83]
	v_mfma_f32_16x16x32_bf16 v[84:87], v[240:243], v[144:147], v[84:87]
	v_mfma_f32_16x16x32_bf16 v[88:91], v[204:207], v[148:151], v[88:91]
	v_mfma_f32_16x16x32_bf16 v[92:95], v[240:243], v[148:151], v[92:95]
	s_waitcnt lgkmcnt(0)
	v_mfma_f32_16x16x32_bf16 v[96:99], v[204:207], v[164:167], v[96:99]
	v_mfma_f32_16x16x32_bf16 v[100:103], v[240:243], v[164:167], v[100:103]
	v_mfma_f32_16x16x32_bf16 v[104:107], v[204:207], v[168:171], v[104:107]
	v_mfma_f32_16x16x32_bf16 v[108:111], v[240:243], v[168:171], v[108:111]
	v_mfma_f32_16x16x32_bf16 v[112:115], v[204:207], v[172:175], v[112:115]
	v_mfma_f32_16x16x32_bf16 v[116:119], v[240:243], v[172:175], v[116:119]
	v_mfma_f32_16x16x32_bf16 v[120:123], v[204:207], v[176:179], v[120:123]
	v_mfma_f32_16x16x32_bf16 v[124:127], v[240:243], v[176:179], v[124:127]
	s_add_i32 s63, s63, 2
	s_cmp_lt_u32 s63, 4
	s_cbranch_scc1 .Lg2_up_loop16
	s_branch .Lg2_up_episel
.Lg2_up_episel:
	s_cmp_ge_u32 s38, 6
	s_cbranch_scc1 .Lg2_up_epiV
	s_lshl_b32 s0, s38, 2
	s_add_i32 s0, s0, s70
	s_mul_hi_u32 s1, s0, 0x55555556
	s_mul_i32 s1, s1, 3
	s_sub_u32 s0, s0, s1
	s_cmp_eq_u32 s0, 2
	s_cbranch_scc1 .Lg2_up_epiR
	s_branch .Lg2_up_epiQ
.Lg2_up_epiR:
	s_nop 7
	s_nop 7
	s_barrier
	v_lshrrev_b32_e32 v137, 4, v163
	v_and_b32_e32 v138, 15, v163
	s_mov_b32 s2, 0x600
	v_mul_lo_u32 v137, v137, s2
	v_lshl_add_u32 v252, v138, 4, v137
	v_lshlrev_b32_e32 v136, 2, v138
	v_add_u32_e32 v136, 0x11000, v136
	ds_read_b32 v164, v136 offset:0
	ds_read_b32 v165, v136 offset:64
	ds_read_b32 v166, v136 offset:128
	ds_read_b32 v167, v136 offset:192
	ds_read_b32 v168, v136 offset:256
	ds_read_b32 v169, v136 offset:320
	ds_read_b32 v170, v136 offset:384
	ds_read_b32 v171, v136 offset:448
	ds_read_b32 v172, v136 offset:512
	ds_read_b32 v173, v136 offset:576
	ds_read_b32 v174, v136 offset:640
	ds_read_b32 v175, v136 offset:704
	ds_read_b32 v176, v136 offset:768
	ds_read_b32 v177, v136 offset:832
	ds_read_b32 v178, v136 offset:896
	ds_read_b32 v179, v136 offset:960
	ds_read_b32 v180, v136 offset:1024
	s_waitcnt lgkmcnt(15)
	v_mul_f32_e32 v0, v0, v164
	v_mul_f32_e32 v1, v1, v164
	v_mul_f32_e32 v2, v2, v164
	v_mul_f32_e32 v3, v3, v164
	v_mul_f32_e32 v4, v4, v164
	v_mul_f32_e32 v5, v5, v164
	v_mul_f32_e32 v6, v6, v164
	v_mul_f32_e32 v7, v7, v164
	s_waitcnt lgkmcnt(15)
	v_mul_f32_e32 v8, v8, v165
	v_mul_f32_e32 v9, v9, v165
	v_mul_f32_e32 v10, v10, v165
	v_mul_f32_e32 v11, v11, v165
	v_mul_f32_e32 v12, v12, v165
	v_mul_f32_e32 v13, v13, v165
	v_mul_f32_e32 v14, v14, v165
	v_mul_f32_e32 v15, v15, v165
	s_waitcnt lgkmcnt(14)
	v_mul_f32_e32 v16, v16, v166
	v_mul_f32_e32 v17, v17, v166
	v_mul_f32_e32 v18, v18, v166
	v_mul_f32_e32 v19, v19, v166
	v_mul_f32_e32 v20, v20, v166
	v_mul_f32_e32 v21, v21, v166
	v_mul_f32_e32 v22, v22, v166
	v_mul_f32_e32 v23, v23, v166
	s_waitcnt lgkmcnt(13)
	v_mul_f32_e32 v24, v24, v167
	v_mul_f32_e32 v25, v25, v167
	v_mul_f32_e32 v26, v26, v167
	v_mul_f32_e32 v27, v27, v167
	v_mul_f32_e32 v28, v28, v167
	v_mul_f32_e32 v29, v29, v167
	v_mul_f32_e32 v30, v30, v167
	v_mul_f32_e32 v31, v31, v167
	s_waitcnt lgkmcnt(12)
	v_mul_f32_e32 v32, v32, v168
	v_mul_f32_e32 v33, v33, v168
	v_mul_f32_e32 v34, v34, v168
	v_mul_f32_e32 v35, v35, v168
	v_mul_f32_e32 v36, v36, v168
	v_mul_f32_e32 v37, v37, v168
	v_mul_f32_e32 v38, v38, v168
	v_mul_f32_e32 v39, v39, v168
	s_waitcnt lgkmcnt(11)
	v_mul_f32_e32 v40, v40, v169
	v_mul_f32_e32 v41, v41, v169
	v_mul_f32_e32 v42, v42, v169
	v_mul_f32_e32 v43, v43, v169
	v_mul_f32_e32 v44, v44, v169
	v_mul_f32_e32 v45, v45, v169
	v_mul_f32_e32 v46, v46, v169
	v_mul_f32_e32 v47, v47, v169
	s_waitcnt lgkmcnt(10)
	v_mul_f32_e32 v48, v48, v170
	v_mul_f32_e32 v49, v49, v170
	v_mul_f32_e32 v50, v50, v170
	v_mul_f32_e32 v51, v51, v170
	v_mul_f32_e32 v52, v52, v170
	v_mul_f32_e32 v53, v53, v170
	v_mul_f32_e32 v54, v54, v170
	v_mul_f32_e32 v55, v55, v170
	s_waitcnt lgkmcnt(9)
	v_mul_f32_e32 v56, v56, v171
	v_mul_f32_e32 v57, v57, v171
	v_mul_f32_e32 v58, v58, v171
	v_mul_f32_e32 v59, v59, v171
	v_mul_f32_e32 v60, v60, v171
	v_mul_f32_e32 v61, v61, v171
	v_mul_f32_e32 v62, v62, v171
	v_mul_f32_e32 v63, v63, v171
	s_waitcnt lgkmcnt(8)
	v_mul_f32_e32 v64, v64, v172
	v_mul_f32_e32 v65, v65, v172
	v_mul_f32_e32 v66, v66, v172
	v_mul_f32_e32 v67, v67, v172
	v_mul_f32_e32 v68, v68, v172
	v_mul_f32_e32 v69, v69, v172
	v_mul_f32_e32 v70, v70, v172
	v_mul_f32_e32 v71, v71, v172
	s_waitcnt lgkmcnt(7)
	v_mul_f32_e32 v72, v72, v173
	v_mul_f32_e32 v73, v73, v173
	v_mul_f32_e32 v74, v74, v173
	v_mul_f32_e32 v75, v75, v173
	v_mul_f32_e32 v76, v76, v173
	v_mul_f32_e32 v77, v77, v173
	v_mul_f32_e32 v78, v78, v173
	v_mul_f32_e32 v79, v79, v173
	s_waitcnt lgkmcnt(6)
	v_mul_f32_e32 v80, v80, v174
	v_mul_f32_e32 v81, v81, v174
	v_mul_f32_e32 v82, v82, v174
	v_mul_f32_e32 v83, v83, v174
	v_mul_f32_e32 v84, v84, v174
	v_mul_f32_e32 v85, v85, v174
	v_mul_f32_e32 v86, v86, v174
	v_mul_f32_e32 v87, v87, v174
	s_waitcnt lgkmcnt(5)
	v_mul_f32_e32 v88, v88, v175
	v_mul_f32_e32 v89, v89, v175
	v_mul_f32_e32 v90, v90, v175
	v_mul_f32_e32 v91, v91, v175
	v_mul_f32_e32 v92, v92, v175
	v_mul_f32_e32 v93, v93, v175
	v_mul_f32_e32 v94, v94, v175
	v_mul_f32_e32 v95, v95, v175
	s_waitcnt lgkmcnt(4)
	v_mul_f32_e32 v96, v96, v176
	v_mul_f32_e32 v97, v97, v176
	v_mul_f32_e32 v98, v98, v176
	v_mul_f32_e32 v99, v99, v176
	v_mul_f32_e32 v100, v100, v176
	v_mul_f32_e32 v101, v101, v176
	v_mul_f32_e32 v102, v102, v176
	v_mul_f32_e32 v103, v103, v176
	s_waitcnt lgkmcnt(3)
	v_mul_f32_e32 v104, v104, v177
	v_mul_f32_e32 v105, v105, v177
	v_mul_f32_e32 v106, v106, v177
	v_mul_f32_e32 v107, v107, v177
	v_mul_f32_e32 v108, v108, v177
	v_mul_f32_e32 v109, v109, v177
	v_mul_f32_e32 v110, v110, v177
	v_mul_f32_e32 v111, v111, v177
	s_waitcnt lgkmcnt(2)
	v_mul_f32_e32 v112, v112, v178
	v_mul_f32_e32 v113, v113, v178
	v_mul_f32_e32 v114, v114, v178
	v_mul_f32_e32 v115, v115, v178
	v_mul_f32_e32 v116, v116, v178
	v_mul_f32_e32 v117, v117, v178
	v_mul_f32_e32 v118, v118, v178
	v_mul_f32_e32 v119, v119, v178
	s_waitcnt lgkmcnt(1)
	v_mul_f32_e32 v120, v120, v179
	v_mul_f32_e32 v121, v121, v179
	v_mul_f32_e32 v122, v122, v179
	v_mul_f32_e32 v123, v123, v179
	v_mul_f32_e32 v124, v124, v179
	v_mul_f32_e32 v125, v125, v179
	v_mul_f32_e32 v126, v126, v179
	v_mul_f32_e32 v127, v127, v179
	s_waitcnt lgkmcnt(0)
	v_mul_f32_e32 v128, v128, v180
	v_mul_f32_e32 v129, v129, v180
	v_mul_f32_e32 v130, v130, v180
	v_mul_f32_e32 v131, v131, v180
	v_mul_f32_e32 v132, v132, v180
	v_mul_f32_e32 v133, v133, v180
	v_mul_f32_e32 v134, v134, v180
	v_mul_f32_e32 v135, v135, v180
	v_and_b32_e32 v148, 15, v163
	v_bfe_u32 v149, v163, 4, 2
	v_cmp_gt_u32_e32 vcc, 2, v149
	s_nop 1
	v_cndmask_b32_e64 v150, 0, 1, vcc
	v_and_b32_e32 v149, 1, v149
	v_lshlrev_b32_e32 v149, 4, v149
	s_add_u32 s2, s26, 0x19dcc000
	s_addc_u32 s3, s27, 0
	s_add_u32 s4, s26, 0x19dcd000
	s_addc_u32 s5, s27, 0
	s_add_i32 s0, s69, 0
	v_add_u32_e32 v140, s0, v148
	v_subrev_u32_e32 v141, 0x2100, v140
	v_cmp_gt_u32_e32 vcc, 0x2100, v140
	s_nop 1
	v_cndmask_b32_e32 v141, v141, v140, vcc
	v_subrev_u32_e32 v142, 0x100, v141
	v_lshrrev_b32_e32 v143, 6, v142
	v_and_b32_e32 v143, 0x7f, v143
	v_and_b32_e32 v140, 63, v142
	v_cmp_eq_u32_e32 vcc, 1, v150
	s_nop 1
	v_cndmask_b32_e32 v143, v140, v143, vcc
	v_cmp_le_u32_e32 vcc, 0x100, v141
	s_nop 1
	v_cndmask_b32_e32 v143, 0, v143, vcc
	v_lshl_add_u32 v151, v143, 5, v149
	global_load_dwordx4 v[164:167], v151, s[2:3]
	global_load_dwordx4 v[168:171], v151, s[4:5]
	s_add_i32 s0, s69, 16
	v_add_u32_e32 v140, s0, v148
	v_subrev_u32_e32 v141, 0x2100, v140
	v_cmp_gt_u32_e32 vcc, 0x2100, v140
	s_nop 1
	v_cndmask_b32_e32 v141, v141, v140, vcc
	v_subrev_u32_e32 v142, 0x100, v141
	v_lshrrev_b32_e32 v143, 6, v142
	v_and_b32_e32 v143, 0x7f, v143
	v_and_b32_e32 v140, 63, v142
	v_cmp_eq_u32_e32 vcc, 1, v150
	s_nop 1
	v_cndmask_b32_e32 v143, v140, v143, vcc
	v_cmp_le_u32_e32 vcc, 0x100, v141
	s_nop 1
	v_cndmask_b32_e32 v143, 0, v143, vcc
	v_lshl_add_u32 v151, v143, 5, v149
	global_load_dwordx4 v[172:175], v151, s[2:3]
	global_load_dwordx4 v[176:179], v151, s[4:5]
	s_waitcnt vmcnt(2)
	v_mul_f32_e32 v152, v4, v168
	v_mul_f32_e32 v153, v4, v164
	v_fma_f32 v4, v0, v168, v153
	v_fma_f32 v0, v0, v164, -v152
	v_mul_f32_e32 v152, v5, v169
	v_mul_f32_e32 v153, v5, v165
	v_fma_f32 v5, v1, v169, v153
	v_fma_f32 v1, v1, v165, -v152
	v_mul_f32_e32 v152, v6, v170
	v_mul_f32_e32 v153, v6, v166
	v_fma_f32 v6, v2, v170, v153
	v_fma_f32 v2, v2, v166, -v152
	v_mul_f32_e32 v152, v7, v171
	v_mul_f32_e32 v153, v7, v167
	v_fma_f32 v7, v3, v171, v153
	v_fma_f32 v3, v3, v167, -v152
	v_cvt_pk_bf16_f32 v0, v0, v1
	v_cvt_pk_bf16_f32 v1, v2, v3
	ds_write_b64 v212, v[0:1] offset:0
	v_cvt_pk_bf16_f32 v4, v4, v5
	v_cvt_pk_bf16_f32 v5, v6, v7
	ds_write_b64 v213, v[4:5] offset:0
	s_add_i32 s0, s69, 32
	v_add_u32_e32 v140, s0, v148
	v_subrev_u32_e32 v141, 0x2100, v140
	v_cmp_gt_u32_e32 vcc, 0x2100, v140
	s_nop 1
	v_cndmask_b32_e32 v141, v141, v140, vcc
	v_subrev_u32_e32 v142, 0x100, v141
	v_lshrrev_b32_e32 v143, 6, v142
	v_and_b32_e32 v143, 0x7f, v143
	v_and_b32_e32 v140, 63, v142
	v_cmp_eq_u32_e32 vcc, 1, v150
	s_nop 1
	v_cndmask_b32_e32 v143, v140, v143, vcc
	v_cmp_le_u32_e32 vcc, 0x100, v141
	s_nop 1
	v_cndmask_b32_e32 v143, 0, v143, vcc
	v_lshl_add_u32 v151, v143, 5, v149
	global_load_dwordx4 v[164:167], v151, s[2:3]
	global_load_dwordx4 v[168:171], v151, s[4:5]
	s_waitcnt vmcnt(2)
	v_mul_f32_e32 v152, v12, v176
	v_mul_f32_e32 v153, v12, v172
	v_fma_f32 v12, v8, v176, v153
	v_fma_f32 v8, v8, v172, -v152
	v_mul_f32_e32 v152, v13, v177
	v_mul_f32_e32 v153, v13, v173
	v_fma_f32 v13, v9, v177, v153
	v_fma_f32 v9, v9, v173, -v152
	v_mul_f32_e32 v152, v14, v178
	v_mul_f32_e32 v153, v14, v174
	v_fma_f32 v14, v10, v178, v153
	v_fma_f32 v10, v10, v174, -v152
	v_mul_f32_e32 v152, v15, v179
	v_mul_f32_e32 v153, v15, v175
	v_fma_f32 v15, v11, v179, v153
	v_fma_f32 v11, v11, v175, -v152
	v_cvt_pk_bf16_f32 v8, v8, v9
	v_cvt_pk_bf16_f32 v9, v10, v11
	ds_write_b64 v212, v[8:9] offset:4096
	v_cvt_pk_bf16_f32 v12, v12, v13
	v_cvt_pk_bf16_f32 v13, v14, v15
	ds_write_b64 v213, v[12:13] offset:4096
	s_add_i32 s0, s69, 48
	v_add_u32_e32 v140, s0, v148
	v_subrev_u32_e32 v141, 0x2100, v140
	v_cmp_gt_u32_e32 vcc, 0x2100, v140
	s_nop 1
	v_cndmask_b32_e32 v141, v141, v140, vcc
	v_subrev_u32_e32 v142, 0x100, v141
	v_lshrrev_b32_e32 v143, 6, v142
	v_and_b32_e32 v143, 0x7f, v143
	v_and_b32_e32 v140, 63, v142
	v_cmp_eq_u32_e32 vcc, 1, v150
	s_nop 1
	v_cndmask_b32_e32 v143, v140, v143, vcc
	v_cmp_le_u32_e32 vcc, 0x100, v141
	s_nop 1
	v_cndmask_b32_e32 v143, 0, v143, vcc
	v_lshl_add_u32 v151, v143, 5, v149
	global_load_dwordx4 v[172:175], v151, s[2:3]
	global_load_dwordx4 v[176:179], v151, s[4:5]
	s_waitcnt vmcnt(2)
	v_mul_f32_e32 v152, v20, v168
	v_mul_f32_e32 v153, v20, v164
	v_fma_f32 v20, v16, v168, v153
	v_fma_f32 v16, v16, v164, -v152
	v_mul_f32_e32 v152, v21, v169
	v_mul_f32_e32 v153, v21, v165
	v_fma_f32 v21, v17, v169, v153
	v_fma_f32 v17, v17, v165, -v152
	v_mul_f32_e32 v152, v22, v170
	v_mul_f32_e32 v153, v22, v166
	v_fma_f32 v22, v18, v170, v153
	v_fma_f32 v18, v18, v166, -v152
	v_mul_f32_e32 v152, v23, v171
	v_mul_f32_e32 v153, v23, v167
	v_fma_f32 v23, v19, v171, v153
	v_fma_f32 v19, v19, v167, -v152
	v_cvt_pk_bf16_f32 v16, v16, v17
	v_cvt_pk_bf16_f32 v17, v18, v19
	ds_write_b64 v212, v[16:17] offset:8192
	v_cvt_pk_bf16_f32 v20, v20, v21
	v_cvt_pk_bf16_f32 v21, v22, v23
	ds_write_b64 v213, v[20:21] offset:8192
	s_add_i32 s0, s69, 64
	v_add_u32_e32 v140, s0, v148
	v_subrev_u32_e32 v141, 0x2100, v140
	v_cmp_gt_u32_e32 vcc, 0x2100, v140
	s_nop 1
	v_cndmask_b32_e32 v141, v141, v140, vcc
	v_subrev_u32_e32 v142, 0x100, v141
	v_lshrrev_b32_e32 v143, 6, v142
	v_and_b32_e32 v143, 0x7f, v143
	v_and_b32_e32 v140, 63, v142
	v_cmp_eq_u32_e32 vcc, 1, v150
	s_nop 1
	v_cndmask_b32_e32 v143, v140, v143, vcc
	v_cmp_le_u32_e32 vcc, 0x100, v141
	s_nop 1
	v_cndmask_b32_e32 v143, 0, v143, vcc
	v_lshl_add_u32 v151, v143, 5, v149
	global_load_dwordx4 v[164:167], v151, s[2:3]
	global_load_dwordx4 v[168:171], v151, s[4:5]
	s_waitcnt vmcnt(2)
	v_mul_f32_e32 v152, v28, v176
	v_mul_f32_e32 v153, v28, v172
	v_fma_f32 v28, v24, v176, v153
	v_fma_f32 v24, v24, v172, -v152
	v_mul_f32_e32 v152, v29, v177
	v_mul_f32_e32 v153, v29, v173
	v_fma_f32 v29, v25, v177, v153
	v_fma_f32 v25, v25, v173, -v152
	v_mul_f32_e32 v152, v30, v178
	v_mul_f32_e32 v153, v30, v174
	v_fma_f32 v30, v26, v178, v153
	v_fma_f32 v26, v26, v174, -v152
	v_mul_f32_e32 v152, v31, v179
	v_mul_f32_e32 v153, v31, v175
	v_fma_f32 v31, v27, v179, v153
	v_fma_f32 v27, v27, v175, -v152
	v_cvt_pk_bf16_f32 v24, v24, v25
	v_cvt_pk_bf16_f32 v25, v26, v27
	ds_write_b64 v212, v[24:25] offset:12288
	v_cvt_pk_bf16_f32 v28, v28, v29
	v_cvt_pk_bf16_f32 v29, v30, v31
	ds_write_b64 v213, v[28:29] offset:12288
	s_add_i32 s0, s69, 80
	v_add_u32_e32 v140, s0, v148
	v_subrev_u32_e32 v141, 0x2100, v140
	v_cmp_gt_u32_e32 vcc, 0x2100, v140
	s_nop 1
	v_cndmask_b32_e32 v141, v141, v140, vcc
	v_subrev_u32_e32 v142, 0x100, v141
	v_lshrrev_b32_e32 v143, 6, v142
	v_and_b32_e32 v143, 0x7f, v143
	v_and_b32_e32 v140, 63, v142
	v_cmp_eq_u32_e32 vcc, 1, v150
	s_nop 1
	v_cndmask_b32_e32 v143, v140, v143, vcc
	v_cmp_le_u32_e32 vcc, 0x100, v141
	s_nop 1
	v_cndmask_b32_e32 v143, 0, v143, vcc
	v_lshl_add_u32 v151, v143, 5, v149
	global_load_dwordx4 v[172:175], v151, s[2:3]
	global_load_dwordx4 v[176:179], v151, s[4:5]
	s_waitcnt vmcnt(2)
	v_mul_f32_e32 v152, v36, v168
	v_mul_f32_e32 v153, v36, v164
	v_fma_f32 v36, v32, v168, v153
	v_fma_f32 v32, v32, v164, -v152
	v_mul_f32_e32 v152, v37, v169
	v_mul_f32_e32 v153, v37, v165
	v_fma_f32 v37, v33, v169, v153
	v_fma_f32 v33, v33, v165, -v152
	v_mul_f32_e32 v152, v38, v170
	v_mul_f32_e32 v153, v38, v166
	v_fma_f32 v38, v34, v170, v153
	v_fma_f32 v34, v34, v166, -v152
	v_mul_f32_e32 v152, v39, v171
	v_mul_f32_e32 v153, v39, v167
	v_fma_f32 v39, v35, v171, v153
	v_fma_f32 v35, v35, v167, -v152
	v_cvt_pk_bf16_f32 v32, v32, v33
	v_cvt_pk_bf16_f32 v33, v34, v35
	ds_write_b64 v212, v[32:33] offset:16384
	v_cvt_pk_bf16_f32 v36, v36, v37
	v_cvt_pk_bf16_f32 v37, v38, v39
	ds_write_b64 v213, v[36:37] offset:16384
	s_add_i32 s0, s69, 96
	v_add_u32_e32 v140, s0, v148
	v_subrev_u32_e32 v141, 0x2100, v140
	v_cmp_gt_u32_e32 vcc, 0x2100, v140
	s_nop 1
	v_cndmask_b32_e32 v141, v141, v140, vcc
	v_subrev_u32_e32 v142, 0x100, v141
	v_lshrrev_b32_e32 v143, 6, v142
	v_and_b32_e32 v143, 0x7f, v143
	v_and_b32_e32 v140, 63, v142
	v_cmp_eq_u32_e32 vcc, 1, v150
	s_nop 1
	v_cndmask_b32_e32 v143, v140, v143, vcc
	v_cmp_le_u32_e32 vcc, 0x100, v141
	s_nop 1
	v_cndmask_b32_e32 v143, 0, v143, vcc
	v_lshl_add_u32 v151, v143, 5, v149
	global_load_dwordx4 v[164:167], v151, s[2:3]
	global_load_dwordx4 v[168:171], v151, s[4:5]
	s_waitcnt vmcnt(2)
	v_mul_f32_e32 v152, v44, v176
	v_mul_f32_e32 v153, v44, v172
	v_fma_f32 v44, v40, v176, v153
	v_fma_f32 v40, v40, v172, -v152
	v_mul_f32_e32 v152, v45, v177
	v_mul_f32_e32 v153, v45, v173
	v_fma_f32 v45, v41, v177, v153
	v_fma_f32 v41, v41, v173, -v152
	v_mul_f32_e32 v152, v46, v178
	v_mul_f32_e32 v153, v46, v174
	v_fma_f32 v46, v42, v178, v153
	v_fma_f32 v42, v42, v174, -v152
	v_mul_f32_e32 v152, v47, v179
	v_mul_f32_e32 v153, v47, v175
	v_fma_f32 v47, v43, v179, v153
	v_fma_f32 v43, v43, v175, -v152
	v_cvt_pk_bf16_f32 v40, v40, v41
	v_cvt_pk_bf16_f32 v41, v42, v43
	ds_write_b64 v212, v[40:41] offset:20480
	v_cvt_pk_bf16_f32 v44, v44, v45
	v_cvt_pk_bf16_f32 v45, v46, v47
	ds_write_b64 v213, v[44:45] offset:20480
	s_add_i32 s0, s69, 112
	v_add_u32_e32 v140, s0, v148
	v_subrev_u32_e32 v141, 0x2100, v140
	v_cmp_gt_u32_e32 vcc, 0x2100, v140
	s_nop 1
	v_cndmask_b32_e32 v141, v141, v140, vcc
	v_subrev_u32_e32 v142, 0x100, v141
	v_lshrrev_b32_e32 v143, 6, v142
	v_and_b32_e32 v143, 0x7f, v143
	v_and_b32_e32 v140, 63, v142
	v_cmp_eq_u32_e32 vcc, 1, v150
	s_nop 1
	v_cndmask_b32_e32 v143, v140, v143, vcc
	v_cmp_le_u32_e32 vcc, 0x100, v141
	s_nop 1
	v_cndmask_b32_e32 v143, 0, v143, vcc
	v_lshl_add_u32 v151, v143, 5, v149
	global_load_dwordx4 v[172:175], v151, s[2:3]
	global_load_dwordx4 v[176:179], v151, s[4:5]
	s_waitcnt vmcnt(2)
	v_mul_f32_e32 v152, v52, v168
	v_mul_f32_e32 v153, v52, v164
	v_fma_f32 v52, v48, v168, v153
	v_fma_f32 v48, v48, v164, -v152
	v_mul_f32_e32 v152, v53, v169
	v_mul_f32_e32 v153, v53, v165
	v_fma_f32 v53, v49, v169, v153
	v_fma_f32 v49, v49, v165, -v152
	v_mul_f32_e32 v152, v54, v170
	v_mul_f32_e32 v153, v54, v166
	v_fma_f32 v54, v50, v170, v153
	v_fma_f32 v50, v50, v166, -v152
	v_mul_f32_e32 v152, v55, v171
	v_mul_f32_e32 v153, v55, v167
	v_fma_f32 v55, v51, v171, v153
	v_fma_f32 v51, v51, v167, -v152
	v_cvt_pk_bf16_f32 v48, v48, v49
	v_cvt_pk_bf16_f32 v49, v50, v51
	ds_write_b64 v212, v[48:49] offset:24576
	v_cvt_pk_bf16_f32 v52, v52, v53
	v_cvt_pk_bf16_f32 v53, v54, v55
	ds_write_b64 v213, v[52:53] offset:24576
	s_add_i32 s0, s69, 128
	v_add_u32_e32 v140, s0, v148
	v_subrev_u32_e32 v141, 0x2100, v140
	v_cmp_gt_u32_e32 vcc, 0x2100, v140
	s_nop 1
	v_cndmask_b32_e32 v141, v141, v140, vcc
	v_subrev_u32_e32 v142, 0x100, v141
	v_lshrrev_b32_e32 v143, 6, v142
	v_and_b32_e32 v143, 0x7f, v143
	v_and_b32_e32 v140, 63, v142
	v_cmp_eq_u32_e32 vcc, 1, v150
	s_nop 1
	v_cndmask_b32_e32 v143, v140, v143, vcc
	v_cmp_le_u32_e32 vcc, 0x100, v141
	s_nop 1
	v_cndmask_b32_e32 v143, 0, v143, vcc
	v_lshl_add_u32 v151, v143, 5, v149
	global_load_dwordx4 v[164:167], v151, s[2:3]
	global_load_dwordx4 v[168:171], v151, s[4:5]
	s_waitcnt vmcnt(2)
	v_mul_f32_e32 v152, v60, v176
	v_mul_f32_e32 v153, v60, v172
	v_fma_f32 v60, v56, v176, v153
	v_fma_f32 v56, v56, v172, -v152
	v_mul_f32_e32 v152, v61, v177
	v_mul_f32_e32 v153, v61, v173
	v_fma_f32 v61, v57, v177, v153
	v_fma_f32 v57, v57, v173, -v152
	v_mul_f32_e32 v152, v62, v178
	v_mul_f32_e32 v153, v62, v174
	v_fma_f32 v62, v58, v178, v153
	v_fma_f32 v58, v58, v174, -v152
	v_mul_f32_e32 v152, v63, v179
	v_mul_f32_e32 v153, v63, v175
	v_fma_f32 v63, v59, v179, v153
	v_fma_f32 v59, v59, v175, -v152
	v_cvt_pk_bf16_f32 v56, v56, v57
	v_cvt_pk_bf16_f32 v57, v58, v59
	ds_write_b64 v212, v[56:57] offset:28672
	v_cvt_pk_bf16_f32 v60, v60, v61
	v_cvt_pk_bf16_f32 v61, v62, v63
	ds_write_b64 v213, v[60:61] offset:28672
	s_add_i32 s0, s69, 144
	v_add_u32_e32 v140, s0, v148
	v_subrev_u32_e32 v141, 0x2100, v140
	v_cmp_gt_u32_e32 vcc, 0x2100, v140
	s_nop 1
	v_cndmask_b32_e32 v141, v141, v140, vcc
	v_subrev_u32_e32 v142, 0x100, v141
	v_lshrrev_b32_e32 v143, 6, v142
	v_and_b32_e32 v143, 0x7f, v143
	v_and_b32_e32 v140, 63, v142
	v_cmp_eq_u32_e32 vcc, 1, v150
	s_nop 1
	v_cndmask_b32_e32 v143, v140, v143, vcc
	v_cmp_le_u32_e32 vcc, 0x100, v141
	s_nop 1
	v_cndmask_b32_e32 v143, 0, v143, vcc
	v_lshl_add_u32 v151, v143, 5, v149
	global_load_dwordx4 v[172:175], v151, s[2:3]
	global_load_dwordx4 v[176:179], v151, s[4:5]
	s_waitcnt vmcnt(2)
	v_mul_f32_e32 v152, v68, v168
	v_mul_f32_e32 v153, v68, v164
	v_fma_f32 v68, v64, v168, v153
	v_fma_f32 v64, v64, v164, -v152
	v_mul_f32_e32 v152, v69, v169
	v_mul_f32_e32 v153, v69, v165
	v_fma_f32 v69, v65, v169, v153
	v_fma_f32 v65, v65, v165, -v152
	v_mul_f32_e32 v152, v70, v170
	v_mul_f32_e32 v153, v70, v166
	v_fma_f32 v70, v66, v170, v153
	v_fma_f32 v66, v66, v166, -v152
	v_mul_f32_e32 v152, v71, v171
	v_mul_f32_e32 v153, v71, v167
	v_fma_f32 v71, v67, v171, v153
	v_fma_f32 v67, v67, v167, -v152
	v_cvt_pk_bf16_f32 v64, v64, v65
	v_cvt_pk_bf16_f32 v65, v66, v67
	ds_write_b64 v253, v[64:65] offset:0
	v_cvt_pk_bf16_f32 v68, v68, v69
	v_cvt_pk_bf16_f32 v69, v70, v71
	ds_write_b64 v254, v[68:69] offset:0
	s_add_i32 s0, s69, 160
	v_add_u32_e32 v140, s0, v148
	v_subrev_u32_e32 v141, 0x2100, v140
	v_cmp_gt_u32_e32 vcc, 0x2100, v140
	s_nop 1
	v_cndmask_b32_e32 v141, v141, v140, vcc
	v_subrev_u32_e32 v142, 0x100, v141
	v_lshrrev_b32_e32 v143, 6, v142
	v_and_b32_e32 v143, 0x7f, v143
	v_and_b32_e32 v140, 63, v142
	v_cmp_eq_u32_e32 vcc, 1, v150
	s_nop 1
	v_cndmask_b32_e32 v143, v140, v143, vcc
	v_cmp_le_u32_e32 vcc, 0x100, v141
	s_nop 1
	v_cndmask_b32_e32 v143, 0, v143, vcc
	v_lshl_add_u32 v151, v143, 5, v149
	global_load_dwordx4 v[164:167], v151, s[2:3]
	global_load_dwordx4 v[168:171], v151, s[4:5]
	s_waitcnt vmcnt(2)
	v_mul_f32_e32 v152, v76, v176
	v_mul_f32_e32 v153, v76, v172
	v_fma_f32 v76, v72, v176, v153
	v_fma_f32 v72, v72, v172, -v152
	v_mul_f32_e32 v152, v77, v177
	v_mul_f32_e32 v153, v77, v173
	v_fma_f32 v77, v73, v177, v153
	v_fma_f32 v73, v73, v173, -v152
	v_mul_f32_e32 v152, v78, v178
	v_mul_f32_e32 v153, v78, v174
	v_fma_f32 v78, v74, v178, v153
	v_fma_f32 v74, v74, v174, -v152
	v_mul_f32_e32 v152, v79, v179
	v_mul_f32_e32 v153, v79, v175
	v_fma_f32 v79, v75, v179, v153
	v_fma_f32 v75, v75, v175, -v152
	v_cvt_pk_bf16_f32 v72, v72, v73
	v_cvt_pk_bf16_f32 v73, v74, v75
	ds_write_b64 v253, v[72:73] offset:4096
	v_cvt_pk_bf16_f32 v76, v76, v77
	v_cvt_pk_bf16_f32 v77, v78, v79
	ds_write_b64 v254, v[76:77] offset:4096
	s_add_i32 s0, s69, 176
	v_add_u32_e32 v140, s0, v148
	v_subrev_u32_e32 v141, 0x2100, v140
	v_cmp_gt_u32_e32 vcc, 0x2100, v140
	s_nop 1
	v_cndmask_b32_e32 v141, v141, v140, vcc
	v_subrev_u32_e32 v142, 0x100, v141
	v_lshrrev_b32_e32 v143, 6, v142
	v_and_b32_e32 v143, 0x7f, v143
	v_and_b32_e32 v140, 63, v142
	v_cmp_eq_u32_e32 vcc, 1, v150
	s_nop 1
	v_cndmask_b32_e32 v143, v140, v143, vcc
	v_cmp_le_u32_e32 vcc, 0x100, v141
	s_nop 1
	v_cndmask_b32_e32 v143, 0, v143, vcc
	v_lshl_add_u32 v151, v143, 5, v149
	global_load_dwordx4 v[172:175], v151, s[2:3]
	global_load_dwordx4 v[176:179], v151, s[4:5]
	s_waitcnt vmcnt(2)
	v_mul_f32_e32 v152, v84, v168
	v_mul_f32_e32 v153, v84, v164
	v_fma_f32 v84, v80, v168, v153
	v_fma_f32 v80, v80, v164, -v152
	v_mul_f32_e32 v152, v85, v169
	v_mul_f32_e32 v153, v85, v165
	v_fma_f32 v85, v81, v169, v153
	v_fma_f32 v81, v81, v165, -v152
	v_mul_f32_e32 v152, v86, v170
	v_mul_f32_e32 v153, v86, v166
	v_fma_f32 v86, v82, v170, v153
	v_fma_f32 v82, v82, v166, -v152
	v_mul_f32_e32 v152, v87, v171
	v_mul_f32_e32 v153, v87, v167
	v_fma_f32 v87, v83, v171, v153
	v_fma_f32 v83, v83, v167, -v152
	v_cvt_pk_bf16_f32 v80, v80, v81
	v_cvt_pk_bf16_f32 v81, v82, v83
	ds_write_b64 v253, v[80:81] offset:8192
	v_cvt_pk_bf16_f32 v84, v84, v85
	v_cvt_pk_bf16_f32 v85, v86, v87
	ds_write_b64 v254, v[84:85] offset:8192
	s_add_i32 s0, s69, 192
	v_add_u32_e32 v140, s0, v148
	v_subrev_u32_e32 v141, 0x2100, v140
	v_cmp_gt_u32_e32 vcc, 0x2100, v140
	s_nop 1
	v_cndmask_b32_e32 v141, v141, v140, vcc
	v_subrev_u32_e32 v142, 0x100, v141
	v_lshrrev_b32_e32 v143, 6, v142
	v_and_b32_e32 v143, 0x7f, v143
	v_and_b32_e32 v140, 63, v142
	v_cmp_eq_u32_e32 vcc, 1, v150
	s_nop 1
	v_cndmask_b32_e32 v143, v140, v143, vcc
	v_cmp_le_u32_e32 vcc, 0x100, v141
	s_nop 1
	v_cndmask_b32_e32 v143, 0, v143, vcc
	v_lshl_add_u32 v151, v143, 5, v149
	global_load_dwordx4 v[164:167], v151, s[2:3]
	global_load_dwordx4 v[168:171], v151, s[4:5]
	s_waitcnt vmcnt(2)
	v_mul_f32_e32 v152, v92, v176
	v_mul_f32_e32 v153, v92, v172
	v_fma_f32 v92, v88, v176, v153
	v_fma_f32 v88, v88, v172, -v152
	v_mul_f32_e32 v152, v93, v177
	v_mul_f32_e32 v153, v93, v173
	v_fma_f32 v93, v89, v177, v153
	v_fma_f32 v89, v89, v173, -v152
	v_mul_f32_e32 v152, v94, v178
	v_mul_f32_e32 v153, v94, v174
	v_fma_f32 v94, v90, v178, v153
	v_fma_f32 v90, v90, v174, -v152
	v_mul_f32_e32 v152, v95, v179
	v_mul_f32_e32 v153, v95, v175
	v_fma_f32 v95, v91, v179, v153
	v_fma_f32 v91, v91, v175, -v152
	v_cvt_pk_bf16_f32 v88, v88, v89
	v_cvt_pk_bf16_f32 v89, v90, v91
	ds_write_b64 v253, v[88:89] offset:12288
	v_cvt_pk_bf16_f32 v92, v92, v93
	v_cvt_pk_bf16_f32 v93, v94, v95
	ds_write_b64 v254, v[92:93] offset:12288
	s_add_i32 s0, s69, 208
	v_add_u32_e32 v140, s0, v148
	v_subrev_u32_e32 v141, 0x2100, v140
	v_cmp_gt_u32_e32 vcc, 0x2100, v140
	s_nop 1
	v_cndmask_b32_e32 v141, v141, v140, vcc
	v_subrev_u32_e32 v142, 0x100, v141
	v_lshrrev_b32_e32 v143, 6, v142
	v_and_b32_e32 v143, 0x7f, v143
	v_and_b32_e32 v140, 63, v142
	v_cmp_eq_u32_e32 vcc, 1, v150
	s_nop 1
	v_cndmask_b32_e32 v143, v140, v143, vcc
	v_cmp_le_u32_e32 vcc, 0x100, v141
	s_nop 1
	v_cndmask_b32_e32 v143, 0, v143, vcc
	v_lshl_add_u32 v151, v143, 5, v149
	global_load_dwordx4 v[172:175], v151, s[2:3]
	global_load_dwordx4 v[176:179], v151, s[4:5]
	s_waitcnt vmcnt(2)
	v_mul_f32_e32 v152, v100, v168
	v_mul_f32_e32 v153, v100, v164
	v_fma_f32 v100, v96, v168, v153
	v_fma_f32 v96, v96, v164, -v152
	v_mul_f32_e32 v152, v101, v169
	v_mul_f32_e32 v153, v101, v165
	v_fma_f32 v101, v97, v169, v153
	v_fma_f32 v97, v97, v165, -v152
	v_mul_f32_e32 v152, v102, v170
	v_mul_f32_e32 v153, v102, v166
	v_fma_f32 v102, v98, v170, v153
	v_fma_f32 v98, v98, v166, -v152
	v_mul_f32_e32 v152, v103, v171
	v_mul_f32_e32 v153, v103, v167
	v_fma_f32 v103, v99, v171, v153
	v_fma_f32 v99, v99, v167, -v152
	v_cvt_pk_bf16_f32 v96, v96, v97
	v_cvt_pk_bf16_f32 v97, v98, v99
	ds_write_b64 v253, v[96:97] offset:16384
	v_cvt_pk_bf16_f32 v100, v100, v101
	v_cvt_pk_bf16_f32 v101, v102, v103
	ds_write_b64 v254, v[100:101] offset:16384
	s_add_i32 s0, s69, 224
	v_add_u32_e32 v140, s0, v148
	v_subrev_u32_e32 v141, 0x2100, v140
	v_cmp_gt_u32_e32 vcc, 0x2100, v140
	s_nop 1
	v_cndmask_b32_e32 v141, v141, v140, vcc
	v_subrev_u32_e32 v142, 0x100, v141
	v_lshrrev_b32_e32 v143, 6, v142
	v_and_b32_e32 v143, 0x7f, v143
	v_and_b32_e32 v140, 63, v142
	v_cmp_eq_u32_e32 vcc, 1, v150
	s_nop 1
	v_cndmask_b32_e32 v143, v140, v143, vcc
	v_cmp_le_u32_e32 vcc, 0x100, v141
	s_nop 1
	v_cndmask_b32_e32 v143, 0, v143, vcc
	v_lshl_add_u32 v151, v143, 5, v149
	global_load_dwordx4 v[164:167], v151, s[2:3]
	global_load_dwordx4 v[168:171], v151, s[4:5]
	s_waitcnt vmcnt(2)
	v_mul_f32_e32 v152, v108, v176
	v_mul_f32_e32 v153, v108, v172
	v_fma_f32 v108, v104, v176, v153
	v_fma_f32 v104, v104, v172, -v152
	v_mul_f32_e32 v152, v109, v177
	v_mul_f32_e32 v153, v109, v173
	v_fma_f32 v109, v105, v177, v153
	v_fma_f32 v105, v105, v173, -v152
	v_mul_f32_e32 v152, v110, v178
	v_mul_f32_e32 v153, v110, v174
	v_fma_f32 v110, v106, v178, v153
	v_fma_f32 v106, v106, v174, -v152
	v_mul_f32_e32 v152, v111, v179
	v_mul_f32_e32 v153, v111, v175
	v_fma_f32 v111, v107, v179, v153
	v_fma_f32 v107, v107, v175, -v152
	v_cvt_pk_bf16_f32 v104, v104, v105
	v_cvt_pk_bf16_f32 v105, v106, v107
	ds_write_b64 v253, v[104:105] offset:20480
	v_cvt_pk_bf16_f32 v108, v108, v109
	v_cvt_pk_bf16_f32 v109, v110, v111
	ds_write_b64 v254, v[108:109] offset:20480
	s_add_i32 s0, s69, 240
	v_add_u32_e32 v140, s0, v148
	v_subrev_u32_e32 v141, 0x2100, v140
	v_cmp_gt_u32_e32 vcc, 0x2100, v140
	s_nop 1
	v_cndmask_b32_e32 v141, v141, v140, vcc
	v_subrev_u32_e32 v142, 0x100, v141
	v_lshrrev_b32_e32 v143, 6, v142
	v_and_b32_e32 v143, 0x7f, v143
	v_and_b32_e32 v140, 63, v142
	v_cmp_eq_u32_e32 vcc, 1, v150
	s_nop 1
	v_cndmask_b32_e32 v143, v140, v143, vcc
	v_cmp_le_u32_e32 vcc, 0x100, v141
	s_nop 1
	v_cndmask_b32_e32 v143, 0, v143, vcc
	v_lshl_add_u32 v151, v143, 5, v149
	global_load_dwordx4 v[172:175], v151, s[2:3]
	global_load_dwordx4 v[176:179], v151, s[4:5]
	s_waitcnt vmcnt(2)
	v_mul_f32_e32 v152, v116, v168
	v_mul_f32_e32 v153, v116, v164
	v_fma_f32 v116, v112, v168, v153
	v_fma_f32 v112, v112, v164, -v152
	v_mul_f32_e32 v152, v117, v169
	v_mul_f32_e32 v153, v117, v165
	v_fma_f32 v117, v113, v169, v153
	v_fma_f32 v113, v113, v165, -v152
	v_mul_f32_e32 v152, v118, v170
	v_mul_f32_e32 v153, v118, v166
	v_fma_f32 v118, v114, v170, v153
	v_fma_f32 v114, v114, v166, -v152
	v_mul_f32_e32 v152, v119, v171
	v_mul_f32_e32 v153, v119, v167
	v_fma_f32 v119, v115, v171, v153
	v_fma_f32 v115, v115, v167, -v152
	v_cvt_pk_bf16_f32 v112, v112, v113
	v_cvt_pk_bf16_f32 v113, v114, v115
	ds_write_b64 v253, v[112:113] offset:24576
	v_cvt_pk_bf16_f32 v116, v116, v117
	v_cvt_pk_bf16_f32 v117, v118, v119
	ds_write_b64 v254, v[116:117] offset:24576
	s_add_i32 s0, s69, 256
	v_add_u32_e32 v140, s0, v148
	v_subrev_u32_e32 v141, 0x2100, v140
	v_cmp_gt_u32_e32 vcc, 0x2100, v140
	s_nop 1
	v_cndmask_b32_e32 v141, v141, v140, vcc
	v_subrev_u32_e32 v142, 0x100, v141
	v_lshrrev_b32_e32 v143, 6, v142
	v_and_b32_e32 v143, 0x7f, v143
	v_and_b32_e32 v140, 63, v142
	v_cmp_eq_u32_e32 vcc, 1, v150
	s_nop 1
	v_cndmask_b32_e32 v143, v140, v143, vcc
	v_cmp_le_u32_e32 vcc, 0x100, v141
	s_nop 1
	v_cndmask_b32_e32 v143, 0, v143, vcc
	v_lshl_add_u32 v151, v143, 5, v149
	global_load_dwordx4 v[164:167], v151, s[2:3]
	global_load_dwordx4 v[168:171], v151, s[4:5]
	s_waitcnt vmcnt(2)
	v_mul_f32_e32 v152, v124, v176
	v_mul_f32_e32 v153, v124, v172
	v_fma_f32 v124, v120, v176, v153
	v_fma_f32 v120, v120, v172, -v152
	v_mul_f32_e32 v152, v125, v177
	v_mul_f32_e32 v153, v125, v173
	v_fma_f32 v125, v121, v177, v153
	v_fma_f32 v121, v121, v173, -v152
	v_mul_f32_e32 v152, v126, v178
	v_mul_f32_e32 v153, v126, v174
	v_fma_f32 v126, v122, v178, v153
	v_fma_f32 v122, v122, v174, -v152
	v_mul_f32_e32 v152, v127, v179
	v_mul_f32_e32 v153, v127, v175
	v_fma_f32 v127, v123, v179, v153
	v_fma_f32 v123, v123, v175, -v152
	v_cvt_pk_bf16_f32 v120, v120, v121
	v_cvt_pk_bf16_f32 v121, v122, v123
	ds_write_b64 v253, v[120:121] offset:28672
	v_cvt_pk_bf16_f32 v124, v124, v125
	v_cvt_pk_bf16_f32 v125, v126, v127
	ds_write_b64 v254, v[124:125] offset:28672
	s_cmp_eq_u32 s65, 0
	s_cbranch_scc1 .Lg2_up_st_lastR
	s_waitcnt vmcnt(0)
	v_mul_f32_e32 v152, v132, v168
	v_mul_f32_e32 v153, v132, v164
	v_fma_f32 v132, v128, v168, v153
	v_fma_f32 v128, v128, v164, -v152
	v_mul_f32_e32 v152, v133, v169
	v_mul_f32_e32 v153, v133, v165
	v_fma_f32 v133, v129, v169, v153
	v_fma_f32 v129, v129, v165, -v152
	v_mul_f32_e32 v152, v134, v170
	v_mul_f32_e32 v153, v134, v166
	v_fma_f32 v134, v130, v170, v153
	v_fma_f32 v130, v130, v166, -v152
	v_mul_f32_e32 v152, v135, v171
	v_mul_f32_e32 v153, v135, v167
	v_fma_f32 v135, v131, v171, v153
	v_fma_f32 v131, v131, v167, -v152
	v_cvt_pk_bf16_f32 v128, v128, v129
	v_cvt_pk_bf16_f32 v129, v130, v131
	ds_write_b64 v253, v[128:129] offset:32768
	v_cvt_pk_bf16_f32 v132, v132, v133
	v_cvt_pk_bf16_f32 v133, v134, v135
	ds_write_b64 v254, v[132:133] offset:32768

.Lg2_up_rd_lastaR:
	s_waitcnt lgkmcnt(15)
	global_store_dwordx4 v252, v[0:3], s[60:61]
	s_add_u32 s60, s60, 0x6000
	s_addc_u32 s61, s61, 0
	s_waitcnt lgkmcnt(14)
	global_store_dwordx4 v252, v[4:7], s[60:61]
	s_add_u32 s60, s60, 0x6000
	s_addc_u32 s61, s61, 0
	s_waitcnt lgkmcnt(13)
	global_store_dwordx4 v252, v[8:11], s[60:61]
	s_add_u32 s60, s60, 0x6000
	s_addc_u32 s61, s61, 0
	s_waitcnt lgkmcnt(12)
	global_store_dwordx4 v252, v[12:15], s[60:61]
	s_add_u32 s60, s60, 0x6000
	s_addc_u32 s61, s61, 0
	s_waitcnt lgkmcnt(11)
	global_store_dwordx4 v252, v[16:19], s[60:61]
	s_add_u32 s60, s60, 0x6000
	s_addc_u32 s61, s61, 0
	s_waitcnt lgkmcnt(10)
	global_store_dwordx4 v252, v[20:23], s[60:61]
	s_add_u32 s60, s60, 0x6000
	s_addc_u32 s61, s61, 0
	s_waitcnt lgkmcnt(9)
	global_store_dwordx4 v252, v[24:27], s[60:61]
	s_add_u32 s60, s60, 0x6000
	s_addc_u32 s61, s61, 0
	s_waitcnt lgkmcnt(8)
	global_store_dwordx4 v252, v[28:31], s[60:61]
	s_add_u32 s60, s60, 0x6000
	s_addc_u32 s61, s61, 0
	s_waitcnt lgkmcnt(7)
	global_store_dwordx4 v252, v[32:35], s[60:61]
	s_add_u32 s60, s60, 0x6000
	s_addc_u32 s61, s61, 0
	s_waitcnt lgkmcnt(6)
	global_store_dwordx4 v252, v[36:39], s[60:61]
	s_add_u32 s60, s60, 0x6000
	s_addc_u32 s61, s61, 0
	s_waitcnt lgkmcnt(5)
	global_store_dwordx4 v252, v[40:43], s[60:61]
	s_add_u32 s60, s60, 0x6000
	s_addc_u32 s61, s61, 0
	s_waitcnt lgkmcnt(4)
	global_store_dwordx4 v252, v[44:47], s[60:61]
	s_add_u32 s60, s60, 0x6000
	s_addc_u32 s61, s61, 0
	s_waitcnt lgkmcnt(3)
	global_store_dwordx4 v252, v[48:51], s[60:61]
	s_add_u32 s60, s60, 0x6000
	s_addc_u32 s61, s61, 0
	s_waitcnt lgkmcnt(2)
	global_store_dwordx4 v252, v[52:55], s[60:61]
	s_add_u32 s60, s60, 0x6000
	s_addc_u32 s61, s61, 0
	s_waitcnt lgkmcnt(1)
	global_store_dwordx4 v252, v[56:59], s[60:61]
	s_add_u32 s60, s60, 0x6000
	s_addc_u32 s61, s61, 0
	s_waitcnt lgkmcnt(0)
	global_store_dwordx4 v252, v[60:63], s[60:61]
	s_add_u32 s60, s60, 0x6000
	s_addc_u32 s61, s61, 0
	s_cmp_eq_u32 s65, 0
	s_cbranch_scc1 .Lg2_up_rd_lastR
	s_waitcnt lgkmcnt(0)
	global_store_dwordx4 v252, v[64:67], s[60:61]
	s_add_u32 s60, s60, 0x6000
	s_addc_u32 s61, s61, 0

.Lg2_up_epiQ:
	s_nop 7
	s_nop 7
	s_barrier
	v_lshrrev_b32_e32 v137, 4, v163
	v_and_b32_e32 v138, 15, v163
	s_mov_b32 s2, 0x600
	v_mul_lo_u32 v137, v137, s2
	v_lshl_add_u32 v252, v138, 4, v137
	v_lshlrev_b32_e32 v136, 2, v138
	v_add_u32_e32 v136, 0x11000, v136
	ds_read_b32 v164, v136 offset:0
	ds_read_b32 v165, v136 offset:64
	ds_read_b32 v166, v136 offset:128
	ds_read_b32 v167, v136 offset:192
	ds_read_b32 v168, v136 offset:256
	ds_read_b32 v169, v136 offset:320
	ds_read_b32 v170, v136 offset:384
	ds_read_b32 v171, v136 offset:448
	ds_read_b32 v172, v136 offset:512
	ds_read_b32 v173, v136 offset:576
	ds_read_b32 v174, v136 offset:640
	ds_read_b32 v175, v136 offset:704
	ds_read_b32 v176, v136 offset:768
	ds_read_b32 v177, v136 offset:832
	ds_read_b32 v178, v136 offset:896
	ds_read_b32 v179, v136 offset:960
	ds_read_b32 v180, v136 offset:1024
	s_waitcnt lgkmcnt(15)
	v_mul_f32_e32 v0, v0, v164
	v_mul_f32_e32 v1, v1, v164
	v_mul_f32_e32 v2, v2, v164
	v_mul_f32_e32 v3, v3, v164
	v_mul_f32_e32 v4, v4, v164
	v_mul_f32_e32 v5, v5, v164
	v_mul_f32_e32 v6, v6, v164
	v_mul_f32_e32 v7, v7, v164
	s_waitcnt lgkmcnt(15)
	v_mul_f32_e32 v8, v8, v165
	v_mul_f32_e32 v9, v9, v165
	v_mul_f32_e32 v10, v10, v165
	v_mul_f32_e32 v11, v11, v165
	v_mul_f32_e32 v12, v12, v165
	v_mul_f32_e32 v13, v13, v165
	v_mul_f32_e32 v14, v14, v165
	v_mul_f32_e32 v15, v15, v165
	s_waitcnt lgkmcnt(14)
	v_mul_f32_e32 v16, v16, v166
	v_mul_f32_e32 v17, v17, v166
	v_mul_f32_e32 v18, v18, v166
	v_mul_f32_e32 v19, v19, v166
	v_mul_f32_e32 v20, v20, v166
	v_mul_f32_e32 v21, v21, v166
	v_mul_f32_e32 v22, v22, v166
	v_mul_f32_e32 v23, v23, v166
	s_waitcnt lgkmcnt(13)
	v_mul_f32_e32 v24, v24, v167
	v_mul_f32_e32 v25, v25, v167
	v_mul_f32_e32 v26, v26, v167
	v_mul_f32_e32 v27, v27, v167
	v_mul_f32_e32 v28, v28, v167
	v_mul_f32_e32 v29, v29, v167
	v_mul_f32_e32 v30, v30, v167
	v_mul_f32_e32 v31, v31, v167
	s_waitcnt lgkmcnt(12)
	v_mul_f32_e32 v32, v32, v168
	v_mul_f32_e32 v33, v33, v168
	v_mul_f32_e32 v34, v34, v168
	v_mul_f32_e32 v35, v35, v168
	v_mul_f32_e32 v36, v36, v168
	v_mul_f32_e32 v37, v37, v168
	v_mul_f32_e32 v38, v38, v168
	v_mul_f32_e32 v39, v39, v168
	s_waitcnt lgkmcnt(11)
	v_mul_f32_e32 v40, v40, v169
	v_mul_f32_e32 v41, v41, v169
	v_mul_f32_e32 v42, v42, v169
	v_mul_f32_e32 v43, v43, v169
	v_mul_f32_e32 v44, v44, v169
	v_mul_f32_e32 v45, v45, v169
	v_mul_f32_e32 v46, v46, v169
	v_mul_f32_e32 v47, v47, v169
	s_waitcnt lgkmcnt(10)
	v_mul_f32_e32 v48, v48, v170
	v_mul_f32_e32 v49, v49, v170
	v_mul_f32_e32 v50, v50, v170
	v_mul_f32_e32 v51, v51, v170
	v_mul_f32_e32 v52, v52, v170
	v_mul_f32_e32 v53, v53, v170
	v_mul_f32_e32 v54, v54, v170
	v_mul_f32_e32 v55, v55, v170
	s_waitcnt lgkmcnt(9)
	v_mul_f32_e32 v56, v56, v171
	v_mul_f32_e32 v57, v57, v171
	v_mul_f32_e32 v58, v58, v171
	v_mul_f32_e32 v59, v59, v171
	v_mul_f32_e32 v60, v60, v171
	v_mul_f32_e32 v61, v61, v171
	v_mul_f32_e32 v62, v62, v171
	v_mul_f32_e32 v63, v63, v171
	s_waitcnt lgkmcnt(8)
	v_mul_f32_e32 v64, v64, v172
	v_mul_f32_e32 v65, v65, v172
	v_mul_f32_e32 v66, v66, v172
	v_mul_f32_e32 v67, v67, v172
	v_mul_f32_e32 v68, v68, v172
	v_mul_f32_e32 v69, v69, v172
	v_mul_f32_e32 v70, v70, v172
	v_mul_f32_e32 v71, v71, v172
	s_waitcnt lgkmcnt(7)
	v_mul_f32_e32 v72, v72, v173
	v_mul_f32_e32 v73, v73, v173
	v_mul_f32_e32 v74, v74, v173
	v_mul_f32_e32 v75, v75, v173
	v_mul_f32_e32 v76, v76, v173
	v_mul_f32_e32 v77, v77, v173
	v_mul_f32_e32 v78, v78, v173
	v_mul_f32_e32 v79, v79, v173
	s_waitcnt lgkmcnt(6)
	v_mul_f32_e32 v80, v80, v174
	v_mul_f32_e32 v81, v81, v174
	v_mul_f32_e32 v82, v82, v174
	v_mul_f32_e32 v83, v83, v174
	v_mul_f32_e32 v84, v84, v174
	v_mul_f32_e32 v85, v85, v174
	v_mul_f32_e32 v86, v86, v174
	v_mul_f32_e32 v87, v87, v174
	s_waitcnt lgkmcnt(5)
	v_mul_f32_e32 v88, v88, v175
	v_mul_f32_e32 v89, v89, v175
	v_mul_f32_e32 v90, v90, v175
	v_mul_f32_e32 v91, v91, v175
	v_mul_f32_e32 v92, v92, v175
	v_mul_f32_e32 v93, v93, v175
	v_mul_f32_e32 v94, v94, v175
	v_mul_f32_e32 v95, v95, v175
	s_waitcnt lgkmcnt(4)
	v_mul_f32_e32 v96, v96, v176
	v_mul_f32_e32 v97, v97, v176
	v_mul_f32_e32 v98, v98, v176
	v_mul_f32_e32 v99, v99, v176
	v_mul_f32_e32 v100, v100, v176
	v_mul_f32_e32 v101, v101, v176
	v_mul_f32_e32 v102, v102, v176
	v_mul_f32_e32 v103, v103, v176
	s_waitcnt lgkmcnt(3)
	v_mul_f32_e32 v104, v104, v177
	v_mul_f32_e32 v105, v105, v177
	v_mul_f32_e32 v106, v106, v177
	v_mul_f32_e32 v107, v107, v177
	v_mul_f32_e32 v108, v108, v177
	v_mul_f32_e32 v109, v109, v177
	v_mul_f32_e32 v110, v110, v177
	v_mul_f32_e32 v111, v111, v177
	s_waitcnt lgkmcnt(2)
	v_mul_f32_e32 v112, v112, v178
	v_mul_f32_e32 v113, v113, v178
	v_mul_f32_e32 v114, v114, v178
	v_mul_f32_e32 v115, v115, v178
	v_mul_f32_e32 v116, v116, v178
	v_mul_f32_e32 v117, v117, v178
	v_mul_f32_e32 v118, v118, v178
	v_mul_f32_e32 v119, v119, v178
	s_waitcnt lgkmcnt(1)
	v_mul_f32_e32 v120, v120, v179
	v_mul_f32_e32 v121, v121, v179
	v_mul_f32_e32 v122, v122, v179
	v_mul_f32_e32 v123, v123, v179
	v_mul_f32_e32 v124, v124, v179
	v_mul_f32_e32 v125, v125, v179
	v_mul_f32_e32 v126, v126, v179
	v_mul_f32_e32 v127, v127, v179
	s_waitcnt lgkmcnt(0)
	v_mul_f32_e32 v128, v128, v180
	v_mul_f32_e32 v129, v129, v180
	v_mul_f32_e32 v130, v130, v180
	v_mul_f32_e32 v131, v131, v180
	v_mul_f32_e32 v132, v132, v180
	v_mul_f32_e32 v133, v133, v180
	v_mul_f32_e32 v134, v134, v180
	v_mul_f32_e32 v135, v135, v180
	v_cvt_pk_bf16_f32 v0, v0, v1
	v_cvt_pk_bf16_f32 v1, v2, v3
	ds_write_b64 v212, v[0:1] offset:0
	v_cvt_pk_bf16_f32 v4, v4, v5
	v_cvt_pk_bf16_f32 v5, v6, v7
	ds_write_b64 v213, v[4:5] offset:0
	v_cvt_pk_bf16_f32 v8, v8, v9
	v_cvt_pk_bf16_f32 v9, v10, v11
	ds_write_b64 v212, v[8:9] offset:4096
	v_cvt_pk_bf16_f32 v12, v12, v13
	v_cvt_pk_bf16_f32 v13, v14, v15
	ds_write_b64 v213, v[12:13] offset:4096
	v_cvt_pk_bf16_f32 v16, v16, v17
	v_cvt_pk_bf16_f32 v17, v18, v19
	ds_write_b64 v212, v[16:17] offset:8192
	v_cvt_pk_bf16_f32 v20, v20, v21
	v_cvt_pk_bf16_f32 v21, v22, v23
	ds_write_b64 v213, v[20:21] offset:8192
	v_cvt_pk_bf16_f32 v24, v24, v25
	v_cvt_pk_bf16_f32 v25, v26, v27
	ds_write_b64 v212, v[24:25] offset:12288
	v_cvt_pk_bf16_f32 v28, v28, v29
	v_cvt_pk_bf16_f32 v29, v30, v31
	ds_write_b64 v213, v[28:29] offset:12288
	v_cvt_pk_bf16_f32 v32, v32, v33
	v_cvt_pk_bf16_f32 v33, v34, v35
	ds_write_b64 v212, v[32:33] offset:16384
	v_cvt_pk_bf16_f32 v36, v36, v37
	v_cvt_pk_bf16_f32 v37, v38, v39
	ds_write_b64 v213, v[36:37] offset:16384
	v_cvt_pk_bf16_f32 v40, v40, v41
	v_cvt_pk_bf16_f32 v41, v42, v43
	ds_write_b64 v212, v[40:41] offset:20480
	v_cvt_pk_bf16_f32 v44, v44, v45
	v_cvt_pk_bf16_f32 v45, v46, v47
	ds_write_b64 v213, v[44:45] offset:20480
	v_cvt_pk_bf16_f32 v48, v48, v49
	v_cvt_pk_bf16_f32 v49, v50, v51
	ds_write_b64 v212, v[48:49] offset:24576
	v_cvt_pk_bf16_f32 v52, v52, v53
	v_cvt_pk_bf16_f32 v53, v54, v55
	ds_write_b64 v213, v[52:53] offset:24576
	v_cvt_pk_bf16_f32 v56, v56, v57
	v_cvt_pk_bf16_f32 v57, v58, v59
	ds_write_b64 v212, v[56:57] offset:28672
	v_cvt_pk_bf16_f32 v60, v60, v61
	v_cvt_pk_bf16_f32 v61, v62, v63
	ds_write_b64 v213, v[60:61] offset:28672
	v_cvt_pk_bf16_f32 v64, v64, v65
	v_cvt_pk_bf16_f32 v65, v66, v67
	ds_write_b64 v253, v[64:65] offset:0
	v_cvt_pk_bf16_f32 v68, v68, v69
	v_cvt_pk_bf16_f32 v69, v70, v71
	ds_write_b64 v254, v[68:69] offset:0
	v_cvt_pk_bf16_f32 v72, v72, v73
	v_cvt_pk_bf16_f32 v73, v74, v75
	ds_write_b64 v253, v[72:73] offset:4096
	v_cvt_pk_bf16_f32 v76, v76, v77
	v_cvt_pk_bf16_f32 v77, v78, v79
	ds_write_b64 v254, v[76:77] offset:4096
	v_cvt_pk_bf16_f32 v80, v80, v81
	v_cvt_pk_bf16_f32 v81, v82, v83
	ds_write_b64 v253, v[80:81] offset:8192
	v_cvt_pk_bf16_f32 v84, v84, v85
	v_cvt_pk_bf16_f32 v85, v86, v87
	ds_write_b64 v254, v[84:85] offset:8192
	v_cvt_pk_bf16_f32 v88, v88, v89
	v_cvt_pk_bf16_f32 v89, v90, v91
	ds_write_b64 v253, v[88:89] offset:12288
	v_cvt_pk_bf16_f32 v92, v92, v93
	v_cvt_pk_bf16_f32 v93, v94, v95
	ds_write_b64 v254, v[92:93] offset:12288
	v_cvt_pk_bf16_f32 v96, v96, v97
	v_cvt_pk_bf16_f32 v97, v98, v99
	ds_write_b64 v253, v[96:97] offset:16384
	v_cvt_pk_bf16_f32 v100, v100, v101
	v_cvt_pk_bf16_f32 v101, v102, v103
	ds_write_b64 v254, v[100:101] offset:16384
	v_cvt_pk_bf16_f32 v104, v104, v105
	v_cvt_pk_bf16_f32 v105, v106, v107
	ds_write_b64 v253, v[104:105] offset:20480
	v_cvt_pk_bf16_f32 v108, v108, v109
	v_cvt_pk_bf16_f32 v109, v110, v111
	ds_write_b64 v254, v[108:109] offset:20480
	v_cvt_pk_bf16_f32 v112, v112, v113
	v_cvt_pk_bf16_f32 v113, v114, v115
	ds_write_b64 v253, v[112:113] offset:24576
	v_cvt_pk_bf16_f32 v116, v116, v117
	v_cvt_pk_bf16_f32 v117, v118, v119
	ds_write_b64 v254, v[116:117] offset:24576
	v_cvt_pk_bf16_f32 v120, v120, v121
	v_cvt_pk_bf16_f32 v121, v122, v123
	ds_write_b64 v253, v[120:121] offset:28672
	v_cvt_pk_bf16_f32 v124, v124, v125
	v_cvt_pk_bf16_f32 v125, v126, v127
	ds_write_b64 v254, v[124:125] offset:28672
	s_cmp_eq_u32 s65, 0
	s_cbranch_scc1 .Lg2_up_st_lastQ
	v_cvt_pk_bf16_f32 v128, v128, v129
	v_cvt_pk_bf16_f32 v129, v130, v131
	ds_write_b64 v253, v[128:129] offset:32768
	v_cvt_pk_bf16_f32 v132, v132, v133
	v_cvt_pk_bf16_f32 v133, v134, v135
	ds_write_b64 v254, v[132:133] offset:32768

.Lg2_up_epiV:
	s_nop 7
	s_nop 7
	s_barrier
	v_lshrrev_b32_e32 v137, 4, v163
	v_and_b32_e32 v138, 15, v163
	s_mov_b32 s2, 0x800
	v_mul_lo_u32 v137, v137, s2
	v_lshl_add_u32 v252, v138, 4, v137
	v_lshlrev_b32_e32 v136, 2, v138
	v_add_u32_e32 v136, 0x11440, v136
	ds_read_b32 v164, v136 offset:0
	ds_read_b32 v165, v136 offset:64
	ds_read_b32 v166, v136 offset:128
	ds_read_b32 v167, v136 offset:192
	ds_read_b32 v168, v136 offset:256
	ds_read_b32 v169, v136 offset:320
	ds_read_b32 v170, v136 offset:384
	ds_read_b32 v171, v136 offset:448
	ds_read_b32 v172, v136 offset:512
	ds_read_b32 v173, v136 offset:576
	ds_read_b32 v174, v136 offset:640
	ds_read_b32 v175, v136 offset:704
	ds_read_b32 v176, v136 offset:768
	ds_read_b32 v177, v136 offset:832
	ds_read_b32 v178, v136 offset:896
	ds_read_b32 v179, v136 offset:960
	ds_read_b32 v180, v136 offset:1024
	s_waitcnt lgkmcnt(15)
	v_mul_f32_e32 v0, v0, v164
	v_mul_f32_e32 v1, v1, v164
	v_mul_f32_e32 v2, v2, v164
	v_mul_f32_e32 v3, v3, v164
	v_mul_f32_e32 v4, v4, v164
	v_mul_f32_e32 v5, v5, v164
	v_mul_f32_e32 v6, v6, v164
	v_mul_f32_e32 v7, v7, v164
	s_waitcnt lgkmcnt(15)
	v_mul_f32_e32 v8, v8, v165
	v_mul_f32_e32 v9, v9, v165
	v_mul_f32_e32 v10, v10, v165
	v_mul_f32_e32 v11, v11, v165
	v_mul_f32_e32 v12, v12, v165
	v_mul_f32_e32 v13, v13, v165
	v_mul_f32_e32 v14, v14, v165
	v_mul_f32_e32 v15, v15, v165
	s_waitcnt lgkmcnt(14)
	v_mul_f32_e32 v16, v16, v166
	v_mul_f32_e32 v17, v17, v166
	v_mul_f32_e32 v18, v18, v166
	v_mul_f32_e32 v19, v19, v166
	v_mul_f32_e32 v20, v20, v166
	v_mul_f32_e32 v21, v21, v166
	v_mul_f32_e32 v22, v22, v166
	v_mul_f32_e32 v23, v23, v166
	s_waitcnt lgkmcnt(13)
	v_mul_f32_e32 v24, v24, v167
	v_mul_f32_e32 v25, v25, v167
	v_mul_f32_e32 v26, v26, v167
	v_mul_f32_e32 v27, v27, v167
	v_mul_f32_e32 v28, v28, v167
	v_mul_f32_e32 v29, v29, v167
	v_mul_f32_e32 v30, v30, v167
	v_mul_f32_e32 v31, v31, v167
	s_waitcnt lgkmcnt(12)
	v_mul_f32_e32 v32, v32, v168
	v_mul_f32_e32 v33, v33, v168
	v_mul_f32_e32 v34, v34, v168
	v_mul_f32_e32 v35, v35, v168
	v_mul_f32_e32 v36, v36, v168
	v_mul_f32_e32 v37, v37, v168
	v_mul_f32_e32 v38, v38, v168
	v_mul_f32_e32 v39, v39, v168
	s_waitcnt lgkmcnt(11)
	v_mul_f32_e32 v40, v40, v169
	v_mul_f32_e32 v41, v41, v169
	v_mul_f32_e32 v42, v42, v169
	v_mul_f32_e32 v43, v43, v169
	v_mul_f32_e32 v44, v44, v169
	v_mul_f32_e32 v45, v45, v169
	v_mul_f32_e32 v46, v46, v169
	v_mul_f32_e32 v47, v47, v169
	s_waitcnt lgkmcnt(10)
	v_mul_f32_e32 v48, v48, v170
	v_mul_f32_e32 v49, v49, v170
	v_mul_f32_e32 v50, v50, v170
	v_mul_f32_e32 v51, v51, v170
	v_mul_f32_e32 v52, v52, v170
	v_mul_f32_e32 v53, v53, v170
	v_mul_f32_e32 v54, v54, v170
	v_mul_f32_e32 v55, v55, v170
	s_waitcnt lgkmcnt(9)
	v_mul_f32_e32 v56, v56, v171
	v_mul_f32_e32 v57, v57, v171
	v_mul_f32_e32 v58, v58, v171
	v_mul_f32_e32 v59, v59, v171
	v_mul_f32_e32 v60, v60, v171
	v_mul_f32_e32 v61, v61, v171
	v_mul_f32_e32 v62, v62, v171
	v_mul_f32_e32 v63, v63, v171
	s_waitcnt lgkmcnt(8)
	v_mul_f32_e32 v64, v64, v172
	v_mul_f32_e32 v65, v65, v172
	v_mul_f32_e32 v66, v66, v172
	v_mul_f32_e32 v67, v67, v172
	v_mul_f32_e32 v68, v68, v172
	v_mul_f32_e32 v69, v69, v172
	v_mul_f32_e32 v70, v70, v172
	v_mul_f32_e32 v71, v71, v172
	s_waitcnt lgkmcnt(7)
	v_mul_f32_e32 v72, v72, v173
	v_mul_f32_e32 v73, v73, v173
	v_mul_f32_e32 v74, v74, v173
	v_mul_f32_e32 v75, v75, v173
	v_mul_f32_e32 v76, v76, v173
	v_mul_f32_e32 v77, v77, v173
	v_mul_f32_e32 v78, v78, v173
	v_mul_f32_e32 v79, v79, v173
	s_waitcnt lgkmcnt(6)
	v_mul_f32_e32 v80, v80, v174
	v_mul_f32_e32 v81, v81, v174
	v_mul_f32_e32 v82, v82, v174
	v_mul_f32_e32 v83, v83, v174
	v_mul_f32_e32 v84, v84, v174
	v_mul_f32_e32 v85, v85, v174
	v_mul_f32_e32 v86, v86, v174
	v_mul_f32_e32 v87, v87, v174
	s_waitcnt lgkmcnt(5)
	v_mul_f32_e32 v88, v88, v175
	v_mul_f32_e32 v89, v89, v175
	v_mul_f32_e32 v90, v90, v175
	v_mul_f32_e32 v91, v91, v175
	v_mul_f32_e32 v92, v92, v175
	v_mul_f32_e32 v93, v93, v175
	v_mul_f32_e32 v94, v94, v175
	v_mul_f32_e32 v95, v95, v175
	s_waitcnt lgkmcnt(4)
	v_mul_f32_e32 v96, v96, v176
	v_mul_f32_e32 v97, v97, v176
	v_mul_f32_e32 v98, v98, v176
	v_mul_f32_e32 v99, v99, v176
	v_mul_f32_e32 v100, v100, v176
	v_mul_f32_e32 v101, v101, v176
	v_mul_f32_e32 v102, v102, v176
	v_mul_f32_e32 v103, v103, v176
	s_waitcnt lgkmcnt(3)
	v_mul_f32_e32 v104, v104, v177
	v_mul_f32_e32 v105, v105, v177
	v_mul_f32_e32 v106, v106, v177
	v_mul_f32_e32 v107, v107, v177
	v_mul_f32_e32 v108, v108, v177
	v_mul_f32_e32 v109, v109, v177
	v_mul_f32_e32 v110, v110, v177
	v_mul_f32_e32 v111, v111, v177
	s_waitcnt lgkmcnt(2)
	v_mul_f32_e32 v112, v112, v178
	v_mul_f32_e32 v113, v113, v178
	v_mul_f32_e32 v114, v114, v178
	v_mul_f32_e32 v115, v115, v178
	v_mul_f32_e32 v116, v116, v178
	v_mul_f32_e32 v117, v117, v178
	v_mul_f32_e32 v118, v118, v178
	v_mul_f32_e32 v119, v119, v178
	s_waitcnt lgkmcnt(1)
	v_mul_f32_e32 v120, v120, v179
	v_mul_f32_e32 v121, v121, v179
	v_mul_f32_e32 v122, v122, v179
	v_mul_f32_e32 v123, v123, v179
	v_mul_f32_e32 v124, v124, v179
	v_mul_f32_e32 v125, v125, v179
	v_mul_f32_e32 v126, v126, v179
	v_mul_f32_e32 v127, v127, v179
	s_waitcnt lgkmcnt(0)
	v_mul_f32_e32 v128, v128, v180
	v_mul_f32_e32 v129, v129, v180
	v_mul_f32_e32 v130, v130, v180
	v_mul_f32_e32 v131, v131, v180
	v_mul_f32_e32 v132, v132, v180
	v_mul_f32_e32 v133, v133, v180
	v_mul_f32_e32 v134, v134, v180
	v_mul_f32_e32 v135, v135, v180
	v_cvt_pk_bf16_f32 v0, v0, v1
	v_cvt_pk_bf16_f32 v1, v2, v3
	ds_write_b64 v212, v[0:1] offset:0
	v_cvt_pk_bf16_f32 v4, v4, v5
	v_cvt_pk_bf16_f32 v5, v6, v7
	ds_write_b64 v213, v[4:5] offset:0
	v_cvt_pk_bf16_f32 v8, v8, v9
	v_cvt_pk_bf16_f32 v9, v10, v11
	ds_write_b64 v212, v[8:9] offset:4096
	v_cvt_pk_bf16_f32 v12, v12, v13
	v_cvt_pk_bf16_f32 v13, v14, v15
	ds_write_b64 v213, v[12:13] offset:4096
	v_cvt_pk_bf16_f32 v16, v16, v17
	v_cvt_pk_bf16_f32 v17, v18, v19
	ds_write_b64 v212, v[16:17] offset:8192
	v_cvt_pk_bf16_f32 v20, v20, v21
	v_cvt_pk_bf16_f32 v21, v22, v23
	ds_write_b64 v213, v[20:21] offset:8192
	v_cvt_pk_bf16_f32 v24, v24, v25
	v_cvt_pk_bf16_f32 v25, v26, v27
	ds_write_b64 v212, v[24:25] offset:12288
	v_cvt_pk_bf16_f32 v28, v28, v29
	v_cvt_pk_bf16_f32 v29, v30, v31
	ds_write_b64 v213, v[28:29] offset:12288
	v_cvt_pk_bf16_f32 v32, v32, v33
	v_cvt_pk_bf16_f32 v33, v34, v35
	ds_write_b64 v212, v[32:33] offset:16384
	v_cvt_pk_bf16_f32 v36, v36, v37
	v_cvt_pk_bf16_f32 v37, v38, v39
	ds_write_b64 v213, v[36:37] offset:16384
	v_cvt_pk_bf16_f32 v40, v40, v41
	v_cvt_pk_bf16_f32 v41, v42, v43
	ds_write_b64 v212, v[40:41] offset:20480
	v_cvt_pk_bf16_f32 v44, v44, v45
	v_cvt_pk_bf16_f32 v45, v46, v47
	ds_write_b64 v213, v[44:45] offset:20480
	v_cvt_pk_bf16_f32 v48, v48, v49
	v_cvt_pk_bf16_f32 v49, v50, v51
	ds_write_b64 v212, v[48:49] offset:24576
	v_cvt_pk_bf16_f32 v52, v52, v53
	v_cvt_pk_bf16_f32 v53, v54, v55
	ds_write_b64 v213, v[52:53] offset:24576
	v_cvt_pk_bf16_f32 v56, v56, v57
	v_cvt_pk_bf16_f32 v57, v58, v59
	ds_write_b64 v212, v[56:57] offset:28672
	v_cvt_pk_bf16_f32 v60, v60, v61
	v_cvt_pk_bf16_f32 v61, v62, v63
	ds_write_b64 v213, v[60:61] offset:28672
	v_cvt_pk_bf16_f32 v64, v64, v65
	v_cvt_pk_bf16_f32 v65, v66, v67
	ds_write_b64 v253, v[64:65] offset:0
	v_cvt_pk_bf16_f32 v68, v68, v69
	v_cvt_pk_bf16_f32 v69, v70, v71
	ds_write_b64 v254, v[68:69] offset:0
	v_cvt_pk_bf16_f32 v72, v72, v73
	v_cvt_pk_bf16_f32 v73, v74, v75
	ds_write_b64 v253, v[72:73] offset:4096
	v_cvt_pk_bf16_f32 v76, v76, v77
	v_cvt_pk_bf16_f32 v77, v78, v79
	ds_write_b64 v254, v[76:77] offset:4096
	v_cvt_pk_bf16_f32 v80, v80, v81
	v_cvt_pk_bf16_f32 v81, v82, v83
	ds_write_b64 v253, v[80:81] offset:8192
	v_cvt_pk_bf16_f32 v84, v84, v85
	v_cvt_pk_bf16_f32 v85, v86, v87
	ds_write_b64 v254, v[84:85] offset:8192
	v_cvt_pk_bf16_f32 v88, v88, v89
	v_cvt_pk_bf16_f32 v89, v90, v91
	ds_write_b64 v253, v[88:89] offset:12288
	v_cvt_pk_bf16_f32 v92, v92, v93
	v_cvt_pk_bf16_f32 v93, v94, v95
	ds_write_b64 v254, v[92:93] offset:12288
	v_cvt_pk_bf16_f32 v96, v96, v97
	v_cvt_pk_bf16_f32 v97, v98, v99
	ds_write_b64 v253, v[96:97] offset:16384
	v_cvt_pk_bf16_f32 v100, v100, v101
	v_cvt_pk_bf16_f32 v101, v102, v103
	ds_write_b64 v254, v[100:101] offset:16384
	v_cvt_pk_bf16_f32 v104, v104, v105
	v_cvt_pk_bf16_f32 v105, v106, v107
	ds_write_b64 v253, v[104:105] offset:20480
	v_cvt_pk_bf16_f32 v108, v108, v109
	v_cvt_pk_bf16_f32 v109, v110, v111
	ds_write_b64 v254, v[108:109] offset:20480
	v_cvt_pk_bf16_f32 v112, v112, v113
	v_cvt_pk_bf16_f32 v113, v114, v115
	ds_write_b64 v253, v[112:113] offset:24576
	v_cvt_pk_bf16_f32 v116, v116, v117
	v_cvt_pk_bf16_f32 v117, v118, v119
	ds_write_b64 v254, v[116:117] offset:24576
	v_cvt_pk_bf16_f32 v120, v120, v121
	v_cvt_pk_bf16_f32 v121, v122, v123
	ds_write_b64 v253, v[120:121] offset:28672
	v_cvt_pk_bf16_f32 v124, v124, v125
	v_cvt_pk_bf16_f32 v125, v126, v127
	ds_write_b64 v254, v[124:125] offset:28672
	s_cmp_eq_u32 s65, 0
	s_cbranch_scc1 .Lg2_up_st_lastV
	v_cvt_pk_bf16_f32 v128, v128, v129
	v_cvt_pk_bf16_f32 v129, v130, v131
	ds_write_b64 v253, v[128:129] offset:32768
	v_cvt_pk_bf16_f32 v132, v132, v133
	v_cvt_pk_bf16_f32 v133, v134, v135
	ds_write_b64 v254, v[132:133] offset:32768

.Lg2_up_next:
	s_add_i32 s64, s64, 1
	s_cmp_lt_u32 s64, 2
	s_cbranch_scc1 .Lg2_up_tile
.Lg2_up_exit:
	s_waitcnt vmcnt(0) lgkmcnt(0)
	s_barrier
	v_mov_b32_e32 v2, 0x10200
	v_mov_b32_e32 v4, s66
	v_mov_b32_e32 v5, s67
	ds_write_b64 v2, v[4:5]
	v_mov_b32_e32 v1, 0
	s_waitcnt vmcnt(0) lgkmcnt(0)
	v_readlane_b32 s56, v244, 40
	v_readlane_b32 s57, v244, 41
	v_readlane_b32 s58, v244, 42
	v_readlane_b32 s59, v244, 43
	v_readlane_b32 s60, v244, 44
	v_readlane_b32 s61, v244, 45
	v_readlane_b32 s62, v244, 46
	v_readlane_b32 s63, v244, 47
	v_readlane_b32 s64, v244, 48
	v_readlane_b32 s65, v244, 49
	v_readlane_b32 s66, v244, 50
	v_readlane_b32 s67, v244, 51
	v_readlane_b32 s68, v244, 52
	v_readlane_b32 s69, v244, 53
	v_readlane_b32 s70, v244, 54
	v_readlane_b32 s71, v244, 55
	v_readlane_b32 s44, v235, 8
	v_readlane_b32 s45, v235, 9
	v_readlane_b32 s56, v246, 0
	s_addk_i32 s56, 0x738
	s_branch .LBB0_555

.LBB0_555:
	s_add_i32 s29, s56, s10
	s_sub_u32 s0, s56, 0x8b8
	s_cmp_lt_u32 s0, 16
	s_cselect_b32 s0, 0x180, 0
	s_sub_i32 s29, s29, s0
	s_cmpk_lt_i32 s29, 0x738
	s_cselect_b64 s[2:3], -1, 0
	s_cmpk_gt_i32 s29, 0x737
	s_cbranch_scc1 .LBB0_561
	s_cmpk_gt_i32 s29, 0x317
	s_mov_b64 s[0:1], -1
	s_cbranch_scc0 .LBB0_558
	s_add_i32 s0, s29, 0xfce8
	s_and_b32 s1, s0, 0xffff
	s_mul_i32 s1, s1, 0xf83f
	s_lshr_b32 s8, s1, 16
	s_lshr_b32 s1, s1, 23
	s_mulk_i32 s1, 0x84
	s_sub_i32 s30, s0, s1
	s_mov_b64 s[0:1], 0
	s_add_u32 s0, s26, s0
	s_addc_u32 s1, s27, s1
	s_add_u32 s4, s0, 0x1e00
	s_addc_u32 s5, s1, 0
	s_mov_b64 s[0:1], 0
	s_add_u32 s0, s26, s0
	s_addc_u32 s1, s27, s1
	s_add_u32 s6, s0, 0xf9c0000
	s_addc_u32 s7, s1, 0
	s_lshl_b32 s0, s30, 7
	s_and_b32 s59, s0, 0xff80
	s_and_b32 s58, s8, 0xff80
	s_mov_b64 s[0:1], 0

.LBB0_792:
	s_or_b64 exec, exec, s[4:5]
	v_readlane_b32 s5, v235, 17
	v_lshrrev_b32_e32 v2, 3, v163
	v_and_b32_e32 v3, 7, v163
	v_lshlrev_b32_e32 v3, 4, v3
	s_movk_i32 s0, 0x84
	v_mul_lo_u32 v6, v2, s0
	v_add_u32_e32 v6, v6, v3
	v_and_b32_e32 v9, 31, v163
	v_lshrrev_b32_e32 v18, 5, v163
	s_movk_i32 s0, 0x108
	v_mul_lo_u32 v7, v9, s0
	v_lshl_add_u32 v7, v18, 2, v7
	v_lshlrev_b32_e32 v21, 2, v2
	s_movk_i32 s0, 0x420
	v_mul_lo_u32 v30, v18, s0
	v_lshl_add_u32 v30, v9, 2, v30
	v_lshrrev_b32_e32 v19, 4, v9
	v_lshlrev_b32_e32 v31, 13, v19
	v_lshrrev_b32_e32 v19, 2, v18
	v_lshl_add_u32 v31, v19, 10, v31
	v_and_b32_e32 v19, 3, v18
	v_lshl_add_u32 v31, v19, 8, v31
	v_and_b32_e32 v19, 15, v9
	v_lshl_add_u32 v31, v19, 4, v31
	v_lshlrev_b32_e32 v9, 2, v9
	v_readlane_b32 s6, v246, 0
	s_add_i32 s31, s6, 0x0
	s_cmp_lt_u32 s31, 96
	s_cbranch_scc1 .Lfs_saa0_q
	s_cmp_lt_u32 s31, 224
	s_cbranch_scc1 .Lfs_saa0_kv
	s_sub_u32 s30, s31, 224
	s_lshr_b32 s4, s30, 8
	s_and_b32 s30, s30, 255
	v_readlane_b32 s0, v235, 4
	v_readlane_b32 s1, v235, 5
	v_readlane_b32 s2, v235, 6
	v_readlane_b32 s3, v235, 7
	s_cmp_eq_u32 s4, 1
	s_cselect_b32 s0, s2, s0
	s_cselect_b32 s1, s3, s1
	s_cmp_eq_u32 s4, 2
	s_cselect_b32 s0, s12, s0
	s_cselect_b32 s1, s13, s1
	s_lshl_b32 s2, s5, 21
	s_add_u32 s0, s0, s2
	s_addc_u32 s1, s1, 0
	s_lshl_b32 s38, s4, 20
	s_add_u32 s38, s38, 0xf20000
	s_movk_i32 s7, 0x1000
	s_movk_i32 s8, 0x400
	s_lshr_b32 s39, s30, 5
	s_lshl_b32 s39, s39, 7
	s_and_b32 s4, s30, 31
	s_mov_b32 s29, 0
	s_branch .Lfs_saa0_j

.Lfs_sab0_j:
	v_mul_f32_e32 v40, v40, v48
	v_mul_f32_e32 v41, v41, v48
	v_mul_f32_e32 v42, v42, v48
	v_mul_f32_e32 v43, v43, v48
	v_mul_f32_e32 v44, v44, v49
	v_mul_f32_e32 v45, v45, v49
	v_mul_f32_e32 v46, v46, v49
	v_mul_f32_e32 v47, v47, v49
	s_barrier
	ds_write2_b32 v6, v40, v41 offset1:1
	ds_write2_b32 v6, v42, v43 offset0:2 offset1:3
	v_add_u32_e32 v19, 0x1080, v6
	ds_write2_b32 v19, v44, v45 offset1:1
	ds_write2_b32 v19, v46, v47 offset0:2 offset1:3
	s_waitcnt lgkmcnt(0)
	s_barrier
	s_cmp_eq_u32 s29, 0
	s_cbranch_scc1 .Lfs_sa_rm0
	ds_read_b32 v22, v30
	ds_read_b32 v23, v30 offset:132
	ds_read_b32 v24, v30 offset:264
	ds_read_b32 v25, v30 offset:396
	ds_read_b32 v26, v30 offset:528
	ds_read_b32 v27, v30 offset:660
	ds_read_b32 v28, v30 offset:792
	ds_read_b32 v29, v30 offset:924
	s_lshl_b32 s30, s4, 14
	s_add_u32 s38, s38, s30
	s_lshl_b32 s30, s39, 4
	s_add_u32 s38, s38, s30
	s_add_u32 s38, s38, 0xeb20000
	s_add_u32 s38, s26, s38
	s_addc_u32 s39, s27, 0
	s_waitcnt lgkmcnt(0)
	v_cvt_pk_bf16_f32 v22, v22, v23
	v_cvt_pk_bf16_f32 v23, v24, v25
	v_cvt_pk_bf16_f32 v24, v26, v27
	v_cvt_pk_bf16_f32 v25, v28, v29
	global_store_dwordx4 v31, v[22:25], s[38:39]
	s_branch .Lfs_sa_st0
.Lfs_sa_rm0:
	s_lshl_b32 s30, s4, 5
	s_mul_i32 s30, s30, s8
	s_add_u32 s38, s38, s30
	s_add_u32 s38, s38, s39
	s_add_u32 s38, s38, 0xeb20000
	s_add_u32 s38, s26, s38
	s_addc_u32 s39, s27, 0
	ds_read_b32 v22, v7
	ds_read_b32 v23, v7 offset:132
	ds_read_b32 v24, v7 offset:32
	ds_read_b32 v25, v7 offset:164
	ds_read_b32 v26, v7 offset:64
	ds_read_b32 v27, v7 offset:196
	ds_read_b32 v28, v7 offset:96
	ds_read_b32 v29, v7 offset:228
	v_mul_lo_u32 v20, v18, s8
	v_add_u32_e32 v20, v20, v9
	s_lshl_b32 s0, s8, 3
	s_waitcnt lgkmcnt(0)
	v_cvt_pk_bf16_f32 v22, v22, v23
	v_cvt_pk_bf16_f32 v24, v24, v25
	v_cvt_pk_bf16_f32 v26, v26, v27
	v_cvt_pk_bf16_f32 v28, v28, v29
	global_store_dword v20, v22, s[38:39]
	s_add_u32 s38, s38, s0
	s_addc_u32 s39, s39, 0
	global_store_dword v20, v24, s[38:39]
	s_add_u32 s38, s38, s0
	s_addc_u32 s39, s39, 0
	global_store_dword v20, v26, s[38:39]
	s_add_u32 s38, s38, s0
	s_addc_u32 s39, s39, 0
	global_store_dword v20, v28, s[38:39]
.Lfs_sa_st0:
	s_add_i32 s31, s6, 0x200
	s_cmp_lt_u32 s31, 992
	s_cbranch_scc0 .Lfs_sa_done
	s_cmp_lt_u32 s31, 96
	s_cbranch_scc1 .Lfs_sab1_q
	s_cmp_lt_u32 s31, 224
	s_cbranch_scc1 .Lfs_sab1_kv
	s_sub_u32 s30, s31, 224
	s_lshr_b32 s4, s30, 8
	s_and_b32 s30, s30, 255
	v_readlane_b32 s0, v235, 4
	v_readlane_b32 s1, v235, 5
	v_readlane_b32 s2, v235, 6
	v_readlane_b32 s3, v235, 7
	s_cmp_eq_u32 s4, 1
	s_cselect_b32 s0, s2, s0
	s_cselect_b32 s1, s3, s1
	s_cmp_eq_u32 s4, 2
	s_cselect_b32 s0, s12, s0
	s_cselect_b32 s1, s13, s1
	s_lshl_b32 s2, s5, 21
	s_add_u32 s0, s0, s2
	s_addc_u32 s1, s1, 0
	s_lshl_b32 s38, s4, 20
	s_add_u32 s38, s38, 0xf20000
	s_movk_i32 s7, 0x1000
	s_movk_i32 s8, 0x400
	s_lshr_b32 s39, s30, 5
	s_lshl_b32 s39, s39, 7
	s_and_b32 s4, s30, 31
	s_mov_b32 s29, 0
	s_branch .Lfs_sab1_j

.Lfs_sab1_j:
	v_mul_f32_e32 v52, v52, v60
	v_mul_f32_e32 v53, v53, v60
	v_mul_f32_e32 v54, v54, v60
	v_mul_f32_e32 v55, v55, v60
	v_mul_f32_e32 v56, v56, v61
	v_mul_f32_e32 v57, v57, v61
	v_mul_f32_e32 v58, v58, v61
	v_mul_f32_e32 v59, v59, v61
	s_barrier
	ds_write2_b32 v6, v52, v53 offset1:1
	ds_write2_b32 v6, v54, v55 offset0:2 offset1:3
	v_add_u32_e32 v19, 0x1080, v6
	ds_write2_b32 v19, v56, v57 offset1:1
	ds_write2_b32 v19, v58, v59 offset0:2 offset1:3
	s_waitcnt lgkmcnt(0)
	s_barrier
	s_cmp_eq_u32 s29, 0
	s_cbranch_scc1 .Lfs_sa_rm1
	ds_read_b32 v22, v30
	ds_read_b32 v23, v30 offset:132
	ds_read_b32 v24, v30 offset:264
	ds_read_b32 v25, v30 offset:396
	ds_read_b32 v26, v30 offset:528
	ds_read_b32 v27, v30 offset:660
	ds_read_b32 v28, v30 offset:792
	ds_read_b32 v29, v30 offset:924
	s_lshl_b32 s30, s4, 14
	s_add_u32 s38, s38, s30
	s_lshl_b32 s30, s39, 4
	s_add_u32 s38, s38, s30
	s_add_u32 s38, s38, 0xeb20000
	s_add_u32 s38, s26, s38
	s_addc_u32 s39, s27, 0
	s_waitcnt lgkmcnt(0)
	v_cvt_pk_bf16_f32 v22, v22, v23
	v_cvt_pk_bf16_f32 v23, v24, v25
	v_cvt_pk_bf16_f32 v24, v26, v27
	v_cvt_pk_bf16_f32 v25, v28, v29
	global_store_dwordx4 v31, v[22:25], s[38:39]
	s_branch .Lfs_sa_st1

.Lfs_sa_st1:
.Lfs_sa_done:
	s_waitcnt vmcnt(0) lgkmcnt(0)
	s_barrier
	s_mov_b32 s0, s26
	s_mov_b32 s1, s27
	s_mov_b64 s[2:3], 0

.LBB0_864:
	s_or_b64 exec, exec, s[4:5]
	s_mov_b32 s5, 0
	v_lshrrev_b32_e32 v2, 3, v163
	v_and_b32_e32 v3, 7, v163
	v_lshlrev_b32_e32 v3, 4, v3
	s_movk_i32 s0, 0x84
	v_mul_lo_u32 v6, v2, s0
	v_add_u32_e32 v6, v6, v3
	v_and_b32_e32 v9, 31, v163
	v_lshrrev_b32_e32 v18, 5, v163
	s_movk_i32 s0, 0x108
	v_mul_lo_u32 v7, v9, s0
	v_lshl_add_u32 v7, v18, 2, v7
	v_lshlrev_b32_e32 v21, 2, v2
	s_movk_i32 s0, 0x420
	v_mul_lo_u32 v30, v18, s0
	v_lshl_add_u32 v30, v9, 2, v30
	v_lshrrev_b32_e32 v19, 4, v9
	v_lshlrev_b32_e32 v31, 13, v19
	v_lshrrev_b32_e32 v19, 2, v18
	v_lshl_add_u32 v31, v19, 10, v31
	v_and_b32_e32 v19, 3, v18
	v_lshl_add_u32 v31, v19, 8, v31
	v_and_b32_e32 v19, 15, v9
	v_lshl_add_u32 v31, v19, 4, v31
	v_lshlrev_b32_e32 v9, 2, v9
	v_readlane_b32 s6, v246, 0
	s_add_i32 s31, s6, 0x0
	s_cmp_lt_u32 s31, 96
	s_cbranch_scc1 .Lfs_sba0_q
	s_cmp_lt_u32 s31, 224
	s_cbranch_scc1 .Lfs_sba0_kv
	s_sub_u32 s30, s31, 224
	s_lshr_b32 s4, s30, 8
	s_and_b32 s30, s30, 255
	v_readlane_b32 s0, v235, 4
	v_readlane_b32 s1, v235, 5
	v_readlane_b32 s2, v235, 6
	v_readlane_b32 s3, v235, 7
	s_cmp_eq_u32 s4, 1
	s_cselect_b32 s0, s2, s0
	s_cselect_b32 s1, s3, s1
	s_cmp_eq_u32 s4, 2
	s_cselect_b32 s0, s12, s0
	s_cselect_b32 s1, s13, s1
	s_lshl_b32 s2, s5, 21
	s_add_u32 s0, s0, s2
	s_addc_u32 s1, s1, 0
	s_lshl_b32 s38, s4, 20
	s_add_u32 s38, s38, 0xf20000
	s_movk_i32 s7, 0x1000
	s_movk_i32 s8, 0x400
	s_lshr_b32 s39, s30, 5
	s_lshl_b32 s39, s39, 7
	s_and_b32 s4, s30, 31
	s_mov_b32 s29, 0
	s_branch .Lfs_sba0_j

	.amdhsa_kernel _Z11mega_kernel6Paramsii
		.amdhsa_group_segment_fixed_size 71808
		.amdhsa_private_segment_fixed_size 0
		.amdhsa_kernarg_size 456
		.amdhsa_user_sgpr_count 2
		.amdhsa_user_sgpr_dispatch_ptr 0
		.amdhsa_user_sgpr_queue_ptr 0
		.amdhsa_user_sgpr_kernarg_segment_ptr 1
		.amdhsa_user_sgpr_dispatch_id 0
		.amdhsa_user_sgpr_kernarg_preload_length 0
		.amdhsa_user_sgpr_kernarg_preload_offset 0
		.amdhsa_user_sgpr_private_segment_size 0
		.amdhsa_uses_dynamic_stack 0
		.amdhsa_enable_private_segment 0
		.amdhsa_system_sgpr_workgroup_id_x 1
		.amdhsa_system_sgpr_workgroup_id_y 0
		.amdhsa_system_sgpr_workgroup_id_z 0
		.amdhsa_system_sgpr_workgroup_info 0
		.amdhsa_system_vgpr_workitem_id 2
		.amdhsa_next_free_vgpr 256
		.amdhsa_next_free_sgpr 100
		.amdhsa_accum_offset 256
		.amdhsa_reserve_vcc 1
		.amdhsa_float_round_mode_32 0
		.amdhsa_float_round_mode_16_64 0
		.amdhsa_float_denorm_mode_32 3
		.amdhsa_float_denorm_mode_16_64 3
		.amdhsa_dx10_clamp 1
		.amdhsa_ieee_mode 1
		.amdhsa_fp16_overflow 0
		.amdhsa_tg_split 0
		.amdhsa_exception_fp_ieee_invalid_op 0
		.amdhsa_exception_fp_denorm_src 0
		.amdhsa_exception_fp_ieee_div_zero 0
		.amdhsa_exception_fp_ieee_overflow 0
		.amdhsa_exception_fp_ieee_underflow 0
		.amdhsa_exception_fp_ieee_inexact 0
		.amdhsa_exception_int_div_zero 0
	.end_amdhsa_kernel

amdhsa.kernels:
  - .agpr_count:     0
    .args:
      - .offset:         0
        .size:           192
        .value_kind:     by_value
      - .offset:         192
        .size:           4
        .value_kind:     by_value
      - .offset:         196
        .size:           4
        .value_kind:     by_value
      - .offset:         200
        .size:           4
        .value_kind:     hidden_block_count_x
      - .offset:         204
        .size:           4
        .value_kind:     hidden_block_count_y
      - .offset:         208
        .size:           4
        .value_kind:     hidden_block_count_z
      - .offset:         212
        .size:           2
        .value_kind:     hidden_group_size_x
      - .offset:         214
        .size:           2
        .value_kind:     hidden_group_size_y
      - .offset:         216
        .size:           2
        .value_kind:     hidden_group_size_z
      - .offset:         218
        .size:           2
        .value_kind:     hidden_remainder_x
      - .offset:         220
        .size:           2
        .value_kind:     hidden_remainder_y
      - .offset:         222
        .size:           2
        .value_kind:     hidden_remainder_z
      - .offset:         240
        .size:           8
        .value_kind:     hidden_global_offset_x
      - .offset:         248
        .size:           8
        .value_kind:     hidden_global_offset_y
      - .offset:         256
        .size:           8
        .value_kind:     hidden_global_offset_z
      - .offset:         264
        .size:           2
        .value_kind:     hidden_grid_dims
      - .offset:         288
        .size:           8
        .value_kind:     hidden_multigrid_sync_arg
    .group_segment_fixed_size: 71808
    .kernarg_segment_align: 8
    .kernarg_segment_size: 456
    .language:       OpenCL C
    .language_version:
      - 2
      - 0
    .max_flat_workgroup_size: 256
    .name:           _Z11mega_kernel6Paramsii
    .private_segment_fixed_size: 0
    .sgpr_count:     106
    .sgpr_spill_count: 281
    .symbol:         _Z11mega_kernel6Paramsii.kd
    .uniform_work_group_size: 1
    .uses_dynamic_stack: false
    .vgpr_count:     256
    .vgpr_spill_count: 0
    .wavefront_size: 64
